# seam 0 without per-WG L2 write-back (adaLN outputs written through) + attention: redundant self-max canonicalisations before fminf removed
# speedup vs baseline: 1.0057x; 1.0057x over previous
; #define LAS __attribute__((address_space(3)))
; __device__ __forceinline__ void attn_unit(LAS unsigned char* lds, const bf16* P, bf16* Y, const float* gq, const float* gk, int b, int h, int qb, int tid, int wid, int lane, ...
;     ...
;                 float kf[8];
; #pragma unroll
;                 for (int i = 0; i < 4; ++i) { kf[2 * i] = blo(kw[hf][i]); kf[2 * i + 1] = bhi(kw[hf][i]); }
;                 float ss = 0.f;
; #pragma unroll
;                 for (int i = 0; i < 8; ++i) ss += kf[i] * kf[i];
;                 ss += __shfl_xor(ss, 1); ss += __shfl_xor(ss, 2); ss += __shfl_xor(ss, 4);
;                 const float rs = __builtin_amdgcn_rsqf(ss * (1.0f / 64.0f) + EPSN);
; #pragma unroll
;                 for (int i = 0; i < 4; ++i) { kf[i] *= rs * gk0[i]; kf[4 + i] *= rs * gk1[i]; }
;                 v4u o; o.x = pk2(kf[0], kf[1]); o.y = pk2(kf[2], kf[3]); o.z = pk2(kf[4], kf[5]); o.w = pk2(kf[6], kf[7]);
;                 *(LAS v4u*)(Ks + (sr + 64 * hf) * 72 + 8 * dc) = o;
; #pragma unroll
;                 for (int i = 0; i < 4; ++i) { Vt[(8 * (dcv + 4 * hf) + 2 * i) * 136 + srv] = (bf16)(vw[hf][i] & 0xffffu); Vt[(8 * (dcv + 4 * hf) + 2 * i + 1) * 136 + srv] = (bf16)(vw[hf][i] >> 16); }
;             }
;         }
;         if (tid == 0) flags[(it + 1) % 3] = 0;
;         LBAR();
;         if (!wdone) {
; #pragma unroll
;             for (int p = 3; p >= 0; --p) {
;                 if (8 * kt + 2 * p <= tg && !wdone) {
;                     float av[2][4];
; #pragma unroll
;                     for (int u = 1; u >= 0; --u) {
;                         const int st = 2 * p + u, sg = 8 * kt + st;
;                         if (sg > tg) {
; #pragma unroll
;                             for (int j = 0; j < 4; ++j) av[u][j] = 0.f;
;                         } else {
;                             const bf16x8 a0 = *(const LAS bf16x8*)(Ks + (16 * st + tq) * 72 + 8 * quad), a1 = *(const LAS bf16x8*)(Ks + (16 * st + tq) * 72 + 32 + 8 * quad);
;                             f32x4 z = (f32x4){0.f, 0.f, 0.f, 0.f};
;                             z = mfma16(a0, Bq0, z); z = mfma16(a1, Bq1, z);
;                             float r[4], be[4];
; #pragma unroll
;                             for (int j = 0; j < 4; ++j) { const float e = fexp2(fminf(z[j], 80.f)); const float rr = frcp(1.0f + e); r[j] = rr; be[j] = e * rr; }
;                             if (sg == tg) {
.LBB0_329:
	v_and_b32_e32 v70, 0xffff0000, v52
	v_lshlrev_b32_e32 v69, 16, v52
	v_mul_f32_e32 v75, v70, v70
	v_lshlrev_b32_e32 v71, 16, v53
	v_fmac_f32_e32 v75, v69, v69
	v_and_b32_e32 v72, 0xffff0000, v53
	v_fmac_f32_e32 v75, v71, v71
	v_lshlrev_b32_e32 v73, 16, v54
	v_fmac_f32_e32 v75, v72, v72
	v_and_b32_e32 v74, 0xffff0000, v54
	v_fmac_f32_e32 v75, v73, v73
	v_and_b32_e32 v52, 0xffff0000, v55
	v_lshlrev_b32_e32 v53, 16, v55
	v_fmac_f32_e32 v75, v74, v74
	v_pk_mul_f32 v[54:55], v[52:53], v[52:53]
	v_lshlrev_b32_e32 v80, 16, v50
	v_add_f32_e32 v55, v55, v75
	v_add_f32_e32 v54, v54, v55
	ds_bpermute_b32 v55, v124, v54
	v_and_b32_e32 v81, 0xffff0000, v50
	v_and_b32_e32 v79, 0xffff0000, v49
	s_waitcnt lgkmcnt(0)
	v_add_f32_e32 v54, v54, v55
	ds_bpermute_b32 v55, v125, v54
	s_waitcnt lgkmcnt(0)
	v_add_f32_e32 v54, v54, v55
	ds_bpermute_b32 v55, v126, v54
	s_waitcnt lgkmcnt(0)
	v_add_f32_e32 v54, v54, v55
	v_fmamk_f32 v54, v54, 0x3c800000, v139
	v_rsq_f32_e32 v75, v54
	s_waitcnt vmcnt(1)
	v_mul_f32_e32 v77, v33, v75
	s_waitcnt vmcnt(0)
	v_mul_f32_e32 v76, v37, v75
	v_mul_f32_e32 v74, v77, v74
	v_and_b32_e32 v77, 0xffff0000, v48
	v_mul_f32_e32 v78, v38, v75
	v_mul_f32_e32 v70, v76, v70
	v_lshlrev_b32_e32 v76, 16, v48
	v_mul_f32_e32 v50, v77, v77
	v_mul_f32_e32 v54, v36, v75
	v_mul_f32_e32 v71, v78, v71
	v_lshlrev_b32_e32 v78, 16, v49
	v_fmac_f32_e32 v50, v76, v76
	v_mul_f32_e32 v69, v54, v69
	v_mul_f32_e32 v54, v34, v75
	v_fmac_f32_e32 v50, v78, v78
	v_mul_f32_e32 v55, v32, v75
	v_mul_f32_e32 v53, v54, v53
	v_mul_f32_e32 v54, v39, v75
	v_fmac_f32_e32 v50, v79, v79
	v_mul_f32_e32 v73, v55, v73
	v_mul_f32_e32 v72, v54, v72
	v_fmac_f32_e32 v50, v80, v80
	v_and_b32_e32 v54, 0xffff0000, v51
	v_lshlrev_b32_e32 v55, 16, v51
	v_fmac_f32_e32 v50, v81, v81
	v_pk_mul_f32 v[48:49], v[54:55], v[54:55]
	s_nop 0
	v_add_f32_e32 v49, v49, v50
	v_add_f32_e32 v50, v48, v49
	ds_bpermute_b32 v51, v124, v50
	v_mul_f32_e32 v48, v35, v75
	v_mul_f32_e32 v52, v48, v52
	v_cvt_pk_bf16_f32 v48, v69, v70
	v_cvt_pk_bf16_f32 v49, v71, v72
	s_waitcnt lgkmcnt(0)
	v_add_f32_e32 v69, v50, v51
	ds_bpermute_b32 v70, v125, v69
	v_cvt_pk_bf16_f32 v50, v73, v74
	v_cvt_pk_bf16_f32 v51, v53, v52
	ds_write_b128 v142, v[48:51]
	ds_write_b16 v127, v44 offset:18432
	ds_write_b16_d16_hi v127, v44 offset:18704
	ds_write_b16 v127, v45 offset:18976
	ds_write_b16_d16_hi v127, v45 offset:19248
	ds_write_b16 v127, v46 offset:19520
	s_waitcnt lgkmcnt(6)
	v_add_f32_e32 v48, v69, v70
	ds_bpermute_b32 v49, v126, v48
	ds_write_b16_d16_hi v127, v46 offset:19792
	ds_write_b16 v127, v47 offset:20064
	ds_write_b16_d16_hi v127, v47 offset:20336
	s_waitcnt lgkmcnt(3)
	v_add_f32_e32 v44, v48, v49
	v_fmamk_f32 v44, v44, 0x3c800000, v139
	v_rsq_f32_e32 v44, v44
	s_nop 0
	v_mul_f32_e32 v45, v36, v44
	v_mul_f32_e32 v46, v32, v44
	v_mul_f32_e32 v47, v37, v44
	v_mul_f32_e32 v45, v45, v76
	v_mul_f32_e32 v46, v46, v80
	v_mul_f32_e32 v47, v47, v77
	v_mul_f32_e32 v48, v33, v44
	v_mul_f32_e32 v49, v38, v44
	v_mul_f32_e32 v50, v34, v44
	v_mul_f32_e32 v51, v39, v44
	v_mul_f32_e32 v44, v35, v44
	v_mul_f32_e32 v48, v48, v81
	v_mul_f32_e32 v49, v49, v78
	v_mul_f32_e32 v50, v50, v55
	v_mul_f32_e32 v51, v51, v79
	v_mul_f32_e32 v52, v44, v54
	v_cvt_pk_bf16_f32 v44, v45, v47
	v_cvt_pk_bf16_f32 v45, v49, v51
	v_cvt_pk_bf16_f32 v46, v46, v48
	v_cvt_pk_bf16_f32 v47, v50, v52
	ds_write_b128 v142, v[44:47] offset:9216
	ds_write_b16 v127, v40 offset:27136
	ds_write_b16_d16_hi v127, v40 offset:27408
	ds_write_b16 v127, v41 offset:27680
	ds_write_b16_d16_hi v127, v41 offset:27952
	ds_write_b16 v127, v42 offset:28224
	ds_write_b16_d16_hi v127, v42 offset:28496
	ds_write_b16 v127, v43 offset:28768
	ds_write_b16_d16_hi v127, v43 offset:29040
	s_mov_b64 s[10:11], exec
	v_readlane_b32 s12, v249, 28
	v_readlane_b32 s13, v249, 29
	s_and_b64 s[12:13], s[10:11], s[12:13]
	s_mov_b64 exec, s[12:13]
	ds_write_b32 v95, v95 offset:35844
	s_or_b64 exec, exec, s[10:11]
	s_waitcnt lgkmcnt(0)
	s_barrier
	s_andn2_b64 vcc, exec, s[0:1]
	s_cbranch_vccnz .LBB0_342
	s_andn2_b64 vcc, exec, s[18:19]
	s_cbranch_vccnz .LBB0_343
	ds_read_b128 v[40:43], v134
	ds_read_b128 v[44:47], v134 offset:64
	s_andn2_b64 vcc, exec, s[20:21]
	s_waitcnt lgkmcnt(1)
	v_mfma_f32_16x16x32_bf16 v[40:43], v[40:43], v[24:27], 0
	s_waitcnt lgkmcnt(0)
	v_mfma_f32_16x16x32_bf16 v[40:43], v[44:47], v[28:31], v[40:43]
	s_nop 7
	v_min_f32_e32 v40, 0x42a00000, v40
	v_min_f32_e32 v41, 0x42a00000, v41
	v_min_f32_e32 v42, 0x42a00000, v42
	v_min_f32_e32 v43, 0x42a00000, v43
	v_exp_f32_e32 v40, v40
	v_exp_f32_e32 v41, v41
	v_exp_f32_e32 v46, v42
	v_exp_f32_e32 v47, v43
	v_add_f32_e32 v42, 1.0, v40
	v_add_f32_e32 v43, 1.0, v41
	v_add_f32_e32 v44, 1.0, v46
	v_add_f32_e32 v45, 1.0, v47
	v_rcp_f32_e32 v48, v42
	v_rcp_f32_e32 v49, v43
	v_rcp_f32_e32 v44, v44
	v_rcp_f32_e32 v45, v45
	v_pk_mul_f32 v[42:43], v[40:41], v[48:49]
	v_pk_mul_f32 v[40:41], v[46:47], v[44:45]
	s_cbranch_vccnz .LBB0_335
	v_mov_b32_e32 v46, v93
	s_nop 0
	v_cmp_lt_i32_e64 s[12:13], v129, v46
	v_cmp_lt_i32_e64 s[14:15], v130, v46
	v_cmp_lt_i32_e64 s[10:11], v128, v46
	s_or_b64 s[12:13], s[14:15], s[12:13]
	v_cmp_lt_i32_e32 vcc, v98, v46
	s_or_b64 s[10:11], s[12:13], s[10:11]
	s_or_b64 vcc, s[10:11], vcc
	v_cndmask_b32_e64 v41, 0, v41, s[14:15]
	v_cndmask_b32_e64 v40, 0, v40, s[12:13]
	v_cndmask_b32_e64 v43, 0, v43, s[10:11]
	v_cndmask_b32_e32 v42, 0, v42, vcc
	v_cndmask_b32_e64 v44, 1.0, v44, s[12:13]
	v_cndmask_b32_e64 v49, 1.0, v49, s[10:11]
	v_cndmask_b32_e32 v48, 1.0, v48, vcc
	v_cndmask_b32_e64 v45, 1.0, v45, s[14:15]

; #define LAS __attribute__((address_space(3)))
; __device__ __forceinline__ float fexp2(float x) { return __builtin_amdgcn_exp2f(x); }
; __device__ __forceinline__ float frcp(float x) { return __builtin_amdgcn_rcpf(x); }
; __device__ __forceinline__ f32x4 mfma16(bf16x8 a, bf16x8 b, f32x4 c) { return __builtin_amdgcn_mfma_f32_16x16x32_bf16(a, b, c, 0, 0, 0); }
; __device__ __forceinline__ void attn_unit(LAS unsigned char* lds, const bf16* P, bf16* Y, const float* gq, const float* gk, int b, int h, int qb, int tid, int wid, int lane, ...
;     ...
;                             const bf16x8 a0 = *(const LAS bf16x8*)(Ks + (16 * st + tq) * 72 + 8 * quad), a1 = *(const LAS bf16x8*)(Ks + (16 * st + tq) * 72 + 32 + 8 * quad);
;                             f32x4 z = (f32x4){0.f, 0.f, 0.f, 0.f};
;                             z = mfma16(a0, Bq0, z); z = mfma16(a1, Bq1, z);
;                             float r[4], be[4];
; #pragma unroll
;                             for (int j = 0; j < 4; ++j) { const float e = fexp2(fminf(z[j], 80.f)); const float rr = frcp(1.0f + e); r[j] = rr; be[j] = e * rr; }
;                             if (sg == tg) {
;                                 int tql = tq; asm volatile("" : "+v"(tql));
; #pragma unroll
;                                 for (int j = 0; j < 4; ++j) if (4 * quad + j >= tql) { r[j] = 1.0f; be[j] = 0.f; }
.LBB0_344:
	ds_read_b128 v[44:47], v136 offset:13824
	ds_read_b128 v[48:51], v136 offset:13888
	s_andn2_b64 vcc, exec, s[16:17]
	s_waitcnt lgkmcnt(1)
	v_mfma_f32_16x16x32_bf16 v[44:47], v[44:47], v[24:27], 0
	s_waitcnt lgkmcnt(0)
	v_mfma_f32_16x16x32_bf16 v[44:47], v[48:51], v[28:31], v[44:47]
	s_nop 7
	v_min_f32_e32 v44, 0x42a00000, v44
	v_min_f32_e32 v45, 0x42a00000, v45
	v_min_f32_e32 v48, 0x42a00000, v46
	v_min_f32_e32 v49, 0x42a00000, v47
	v_exp_f32_e32 v46, v44
	v_exp_f32_e32 v47, v45
	v_exp_f32_e32 v52, v48
	v_exp_f32_e32 v53, v49
	v_add_f32_e32 v44, 1.0, v46
	v_add_f32_e32 v45, 1.0, v47
	v_add_f32_e32 v48, 1.0, v52
	v_add_f32_e32 v49, 1.0, v53
	v_rcp_f32_e32 v50, v44
	v_rcp_f32_e32 v51, v45
	v_rcp_f32_e32 v44, v48
	v_rcp_f32_e32 v45, v49
	v_pk_mul_f32 v[48:49], v[46:47], v[50:51]
	v_pk_mul_f32 v[46:47], v[52:53], v[44:45]
	s_cbranch_vccnz .LBB0_346
	v_mov_b32_e32 v52, v93
	s_nop 0
	v_cmp_lt_i32_e64 s[12:13], v129, v52
	v_cmp_lt_i32_e64 s[14:15], v130, v52
	v_cmp_lt_i32_e64 s[10:11], v128, v52
	s_or_b64 s[12:13], s[14:15], s[12:13]
	v_cmp_lt_i32_e32 vcc, v98, v52
	s_or_b64 s[10:11], s[12:13], s[10:11]
	s_or_b64 vcc, s[10:11], vcc
	v_cndmask_b32_e64 v47, 0, v47, s[14:15]
	v_cndmask_b32_e64 v46, 0, v46, s[12:13]
	v_cndmask_b32_e64 v49, 0, v49, s[10:11]
	v_cndmask_b32_e32 v48, 0, v48, vcc
	v_cndmask_b32_e64 v44, 1.0, v44, s[12:13]
	v_cndmask_b32_e64 v51, 1.0, v51, s[10:11]
	v_cndmask_b32_e32 v50, 1.0, v50, vcc
	v_cndmask_b32_e64 v45, 1.0, v45, s[14:15]

; #define LAS __attribute__((address_space(3)))
; __device__ __forceinline__ float fexp2(float x) { return __builtin_amdgcn_exp2f(x); }
; __device__ __forceinline__ float frcp(float x) { return __builtin_amdgcn_rcpf(x); }
; __device__ __forceinline__ f32x4 mfma16(bf16x8 a, bf16x8 b, f32x4 c) { return __builtin_amdgcn_mfma_f32_16x16x32_bf16(a, b, c, 0, 0, 0); }
; #define LBAR() do { asm volatile("s_waitcnt lgkmcnt(0)" ::: "memory"); __builtin_amdgcn_s_barrier(); asm volatile("" ::: "memory"); } while (0)
; __device__ __forceinline__ void attn_unit(LAS unsigned char* lds, const bf16* P, bf16* Y, const float* gq, const float* gk, int b, int h, int qb, int tid, int wid, int lane, ...
;     ...
;         if (tid == 0) flags[(it + 1) % 3] = 0;
;         LBAR();
;         if (!wdone) {
; #pragma unroll
;             for (int p = 3; p >= 0; --p) {
;                 if (8 * kt + 2 * p <= tg && !wdone) {
;                     float av[2][4];
; #pragma unroll
;                     for (int u = 1; u >= 0; --u) {
;                         const int st = 2 * p + u, sg = 8 * kt + st;
;                         if (sg > tg) {
; #pragma unroll
;                             for (int j = 0; j < 4; ++j) av[u][j] = 0.f;
;                         } else {
;                             const bf16x8 a0 = *(const LAS bf16x8*)(Ks + (16 * st + tq) * 72 + 8 * quad), a1 = *(const LAS bf16x8*)(Ks + (16 * st + tq) * 72 + 32 + 8 * quad);
;                             f32x4 z = (f32x4){0.f, 0.f, 0.f, 0.f};
;                             z = mfma16(a0, Bq0, z); z = mfma16(a1, Bq1, z);
;                             float r[4], be[4];
; #pragma unroll
;                             for (int j = 0; j < 4; ++j) { const float e = fexp2(fminf(z[j], 80.f)); const float rr = frcp(1.0f + e); r[j] = rr; be[j] = e * rr; }
;                             if (sg == tg) {
;                                 int tql = tq; asm volatile("" : "+v"(tql));
; #pragma unroll
;                                 for (int j = 0; j < 4; ++j) if (4 * quad + j >= tql) { r[j] = 1.0f; be[j] = 0.f; }
.LBB0_385:
	s_or_b64 exec, exec, s[12:13]
	s_xor_b64 s[12:13], s[10:11], -1
	s_mul_hi_u32 s10, s71, 0xaaaaaaab
	s_waitcnt lgkmcnt(0)
	s_barrier
	s_lshr_b32 s81, s10, 1
	s_mul_i32 s81, s81, -12
	s_mov_b64 s[10:11], -1
	s_and_saveexec_b64 s[64:65], s[12:13]
	s_cbranch_execz .LBB0_473
	s_add_i32 s82, s37, s78
	s_add_i32 s10, s82, 0x76
	s_cmp_gt_u32 s10, s36
	s_mov_b64 s[10:11], 0
	s_cbranch_scc1 .LBB0_407
	s_add_i32 s10, s82, 0x77
	s_cmp_gt_u32 s10, s36
	v_mov_b32_e32 v59, 0
	s_cbranch_scc1 .LBB0_397
	ds_read_b128 v[56:59], v134
	ds_read_b128 v[60:63], v134 offset:64
	s_cmp_lg_u32 s50, s78
	s_waitcnt lgkmcnt(1)
	v_mfma_f32_16x16x32_bf16 v[56:59], v[56:59], v[24:27], 0
	s_waitcnt lgkmcnt(0)
	v_mfma_f32_16x16x32_bf16 v[56:59], v[60:63], v[28:31], v[56:59]
	s_nop 7
	v_min_f32_e32 v56, 0x42a00000, v56
	v_min_f32_e32 v57, 0x42a00000, v57
	v_min_f32_e32 v60, 0x42a00000, v58
	v_min_f32_e32 v61, 0x42a00000, v59
	v_exp_f32_e32 v58, v56
	v_exp_f32_e32 v59, v57
	v_exp_f32_e32 v60, v60
	v_exp_f32_e32 v61, v61
	v_add_f32_e32 v56, 1.0, v58
	v_add_f32_e32 v57, 1.0, v59
	v_add_f32_e32 v64, 1.0, v60
	v_add_f32_e32 v65, 1.0, v61
	v_rcp_f32_e32 v62, v56
	v_rcp_f32_e32 v63, v57
	v_rcp_f32_e32 v56, v64
	v_rcp_f32_e32 v57, v65
	v_pk_mul_f32 v[58:59], v[58:59], v[62:63]
	v_pk_mul_f32 v[60:61], v[60:61], v[56:57]
	s_cbranch_scc1 .LBB0_390
	v_mov_b32_e32 v64, v93
	s_nop 0
	v_cmp_lt_i32_e64 s[12:13], v129, v64
	v_cmp_lt_i32_e64 s[14:15], v130, v64
	v_cmp_lt_i32_e64 s[10:11], v128, v64
	s_or_b64 s[12:13], s[14:15], s[12:13]
	v_cmp_lt_i32_e32 vcc, v98, v64
	s_or_b64 s[10:11], s[12:13], s[10:11]
	s_or_b64 vcc, s[10:11], vcc
	v_cndmask_b32_e64 v61, 0, v61, s[14:15]
	v_cndmask_b32_e64 v60, 0, v60, s[12:13]
	v_cndmask_b32_e64 v59, 0, v59, s[10:11]
	v_cndmask_b32_e32 v58, 0, v58, vcc
	v_cndmask_b32_e64 v56, 1.0, v56, s[12:13]
	v_cndmask_b32_e64 v63, 1.0, v63, s[10:11]
	v_cndmask_b32_e32 v62, 1.0, v62, vcc
	v_cndmask_b32_e64 v57, 1.0, v57, s[14:15]

; #define LAS __attribute__((address_space(3)))
; __device__ __forceinline__ float fexp2(float x) { return __builtin_amdgcn_exp2f(x); }
; __device__ __forceinline__ float frcp(float x) { return __builtin_amdgcn_rcpf(x); }
; __device__ __forceinline__ f32x4 mfma16(bf16x8 a, bf16x8 b, f32x4 c) { return __builtin_amdgcn_mfma_f32_16x16x32_bf16(a, b, c, 0, 0, 0); }
; __device__ __forceinline__ void attn_unit(LAS unsigned char* lds, const bf16* P, bf16* Y, const float* gq, const float* gk, int b, int h, int qb, int tid, int wid, int lane, ...
;     ...
;                         const int st = 2 * p + u, sg = 8 * kt + st;
;                         if (sg > tg) {
; #pragma unroll
;                             for (int j = 0; j < 4; ++j) av[u][j] = 0.f;
;                         } else {
;                             const bf16x8 a0 = *(const LAS bf16x8*)(Ks + (16 * st + tq) * 72 + 8 * quad), a1 = *(const LAS bf16x8*)(Ks + (16 * st + tq) * 72 + 32 + 8 * quad);
;                             f32x4 z = (f32x4){0.f, 0.f, 0.f, 0.f};
;                             z = mfma16(a0, Bq0, z); z = mfma16(a1, Bq1, z);
;                             float r[4], be[4];
; #pragma unroll
;                             for (int j = 0; j < 4; ++j) { const float e = fexp2(fminf(z[j], 80.f)); const float rr = frcp(1.0f + e); r[j] = rr; be[j] = e * rr; }
;                             if (sg == tg) {
;                                 int tql = tq; asm volatile("" : "+v"(tql));
; #pragma unroll
;                                 for (int j = 0; j < 4; ++j) if (4 * quad + j >= tql) { r[j] = 1.0f; be[j] = 0.f; }
.LBB0_398:
	ds_read_b128 v[60:63], v136 offset:13824
	ds_read_b128 v[64:67], v136 offset:13888
	s_cmp_lg_u32 s51, s78
	s_waitcnt lgkmcnt(1)
	v_mfma_f32_16x16x32_bf16 v[60:63], v[60:63], v[24:27], 0
	s_waitcnt lgkmcnt(0)
	v_mfma_f32_16x16x32_bf16 v[60:63], v[64:67], v[28:31], v[60:63]
	s_nop 7
	v_min_f32_e32 v60, 0x42a00000, v60
	v_min_f32_e32 v61, 0x42a00000, v61
	v_min_f32_e32 v64, 0x42a00000, v62
	v_min_f32_e32 v65, 0x42a00000, v63
	v_exp_f32_e32 v62, v60
	v_exp_f32_e32 v63, v61
	v_exp_f32_e32 v84, v64
	v_exp_f32_e32 v85, v65
	v_add_f32_e32 v60, 1.0, v62
	v_add_f32_e32 v61, 1.0, v63
	v_add_f32_e32 v64, 1.0, v84
	v_add_f32_e32 v65, 1.0, v85
	v_rcp_f32_e32 v66, v60
	v_rcp_f32_e32 v67, v61
	v_rcp_f32_e32 v60, v64
	v_rcp_f32_e32 v61, v65
	v_pk_mul_f32 v[64:65], v[62:63], v[66:67]
	v_pk_mul_f32 v[62:63], v[84:85], v[60:61]
	s_cbranch_scc1 .LBB0_400
	v_mov_b32_e32 v84, v93
	s_nop 0
	v_cmp_lt_i32_e64 s[12:13], v129, v84
	v_cmp_lt_i32_e64 s[14:15], v130, v84
	v_cmp_lt_i32_e64 s[10:11], v128, v84
	s_or_b64 s[12:13], s[14:15], s[12:13]
	v_cmp_lt_i32_e32 vcc, v98, v84
	s_or_b64 s[10:11], s[12:13], s[10:11]
	s_or_b64 vcc, s[10:11], vcc
	v_cndmask_b32_e64 v63, 0, v63, s[14:15]
	v_cndmask_b32_e64 v62, 0, v62, s[12:13]
	v_cndmask_b32_e64 v65, 0, v65, s[10:11]
	v_cndmask_b32_e32 v64, 0, v64, vcc
	v_cndmask_b32_e64 v60, 1.0, v60, s[12:13]
	v_cndmask_b32_e64 v67, 1.0, v67, s[10:11]
	v_cndmask_b32_e32 v66, 1.0, v66, vcc
	v_cndmask_b32_e64 v61, 1.0, v61, s[14:15]

; #define LAS __attribute__((address_space(3)))
; __device__ __forceinline__ float fexp2(float x) { return __builtin_amdgcn_exp2f(x); }
; __device__ __forceinline__ float frcp(float x) { return __builtin_amdgcn_rcpf(x); }
; __device__ __forceinline__ f32x4 mfma16(bf16x8 a, bf16x8 b, f32x4 c) { return __builtin_amdgcn_mfma_f32_16x16x32_bf16(a, b, c, 0, 0, 0); }
; __device__ __forceinline__ void attn_unit(LAS unsigned char* lds, const bf16* P, bf16* Y, const float* gq, const float* gk, int b, int h, int qb, int tid, int wid, int lane, ...
;     ...
;                         const int st = 2 * p + u, sg = 8 * kt + st;
;                         if (sg > tg) {
; #pragma unroll
;                             for (int j = 0; j < 4; ++j) av[u][j] = 0.f;
;                         } else {
;                             const bf16x8 a0 = *(const LAS bf16x8*)(Ks + (16 * st + tq) * 72 + 8 * quad), a1 = *(const LAS bf16x8*)(Ks + (16 * st + tq) * 72 + 32 + 8 * quad);
;                             f32x4 z = (f32x4){0.f, 0.f, 0.f, 0.f};
;                             z = mfma16(a0, Bq0, z); z = mfma16(a1, Bq1, z);
;                             float r[4], be[4];
; #pragma unroll
;                             for (int j = 0; j < 4; ++j) { const float e = fexp2(fminf(z[j], 80.f)); const float rr = frcp(1.0f + e); r[j] = rr; be[j] = e * rr; }
;                             if (sg == tg) {
;                                 int tql = tq; asm volatile("" : "+v"(tql));
; #pragma unroll
;                                 for (int j = 0; j < 4; ++j) if (4 * quad + j >= tql) { r[j] = 1.0f; be[j] = 0.f; }
.LBB0_407:
	s_add_i32 s12, s82, 0x74
	s_cmp_gt_u32 s12, s36
	s_cselect_b64 s[12:13], -1, 0
	s_or_b64 s[12:13], s[12:13], s[10:11]
	s_and_b64 vcc, exec, s[12:13]
	s_cbranch_vccnz .LBB0_428
	s_add_i32 s10, s82, 0x75
	s_cmp_gt_u32 s10, s36
	v_mov_b32_e32 v59, 0
	s_cbranch_scc1 .LBB0_418
	ds_read_b128 v[56:59], v136 offset:11520
	ds_read_b128 v[60:63], v136 offset:11584
	s_cmp_lg_u32 s48, s78
	s_waitcnt lgkmcnt(1)
	v_mfma_f32_16x16x32_bf16 v[56:59], v[56:59], v[24:27], 0
	s_waitcnt lgkmcnt(0)
	v_mfma_f32_16x16x32_bf16 v[56:59], v[60:63], v[28:31], v[56:59]
	s_nop 7
	v_min_f32_e32 v56, 0x42a00000, v56
	v_min_f32_e32 v57, 0x42a00000, v57
	v_min_f32_e32 v60, 0x42a00000, v58
	v_min_f32_e32 v61, 0x42a00000, v59
	v_exp_f32_e32 v58, v56
	v_exp_f32_e32 v59, v57
	v_exp_f32_e32 v60, v60
	v_exp_f32_e32 v61, v61
	v_add_f32_e32 v56, 1.0, v58
	v_add_f32_e32 v57, 1.0, v59
	v_add_f32_e32 v64, 1.0, v60
	v_add_f32_e32 v65, 1.0, v61
	v_rcp_f32_e32 v62, v56
	v_rcp_f32_e32 v63, v57
	v_rcp_f32_e32 v56, v64
	v_rcp_f32_e32 v57, v65
	v_pk_mul_f32 v[58:59], v[58:59], v[62:63]
	v_pk_mul_f32 v[60:61], v[60:61], v[56:57]
	s_cbranch_scc1 .LBB0_411
	v_mov_b32_e32 v64, v93
	s_nop 0
	v_cmp_lt_i32_e64 s[12:13], v129, v64
	v_cmp_lt_i32_e64 s[14:15], v130, v64
	v_cmp_lt_i32_e64 s[10:11], v128, v64
	s_or_b64 s[12:13], s[14:15], s[12:13]
	v_cmp_lt_i32_e32 vcc, v98, v64
	s_or_b64 s[10:11], s[12:13], s[10:11]
	s_or_b64 vcc, s[10:11], vcc
	v_cndmask_b32_e64 v61, 0, v61, s[14:15]
	v_cndmask_b32_e64 v60, 0, v60, s[12:13]
	v_cndmask_b32_e64 v59, 0, v59, s[10:11]
	v_cndmask_b32_e32 v58, 0, v58, vcc
	v_cndmask_b32_e64 v56, 1.0, v56, s[12:13]
	v_cndmask_b32_e64 v63, 1.0, v63, s[10:11]
	v_cndmask_b32_e32 v62, 1.0, v62, vcc
	v_cndmask_b32_e64 v57, 1.0, v57, s[14:15]

; #define LAS __attribute__((address_space(3)))
; __device__ __forceinline__ float fexp2(float x) { return __builtin_amdgcn_exp2f(x); }
; __device__ __forceinline__ float frcp(float x) { return __builtin_amdgcn_rcpf(x); }
; __device__ __forceinline__ f32x4 mfma16(bf16x8 a, bf16x8 b, f32x4 c) { return __builtin_amdgcn_mfma_f32_16x16x32_bf16(a, b, c, 0, 0, 0); }
; __device__ __forceinline__ void attn_unit(LAS unsigned char* lds, const bf16* P, bf16* Y, const float* gq, const float* gk, int b, int h, int qb, int tid, int wid, int lane, ...
;     ...
;                         const int st = 2 * p + u, sg = 8 * kt + st;
;                         if (sg > tg) {
; #pragma unroll
;                             for (int j = 0; j < 4; ++j) av[u][j] = 0.f;
;                         } else {
;                             const bf16x8 a0 = *(const LAS bf16x8*)(Ks + (16 * st + tq) * 72 + 8 * quad), a1 = *(const LAS bf16x8*)(Ks + (16 * st + tq) * 72 + 32 + 8 * quad);
;                             f32x4 z = (f32x4){0.f, 0.f, 0.f, 0.f};
;                             z = mfma16(a0, Bq0, z); z = mfma16(a1, Bq1, z);
;                             float r[4], be[4];
; #pragma unroll
;                             for (int j = 0; j < 4; ++j) { const float e = fexp2(fminf(z[j], 80.f)); const float rr = frcp(1.0f + e); r[j] = rr; be[j] = e * rr; }
;                             if (sg == tg) {
;                                 int tql = tq; asm volatile("" : "+v"(tql));
; #pragma unroll
;                                 for (int j = 0; j < 4; ++j) if (4 * quad + j >= tql) { r[j] = 1.0f; be[j] = 0.f; }
.LBB0_419:
	ds_read_b128 v[60:63], v136 offset:9216
	ds_read_b128 v[64:67], v136 offset:9280
	s_cmp_lg_u32 s49, s78
	s_waitcnt lgkmcnt(1)
	v_mfma_f32_16x16x32_bf16 v[60:63], v[60:63], v[24:27], 0
	s_waitcnt lgkmcnt(0)
	v_mfma_f32_16x16x32_bf16 v[60:63], v[64:67], v[28:31], v[60:63]
	s_nop 7
	v_min_f32_e32 v60, 0x42a00000, v60
	v_min_f32_e32 v61, 0x42a00000, v61
	v_min_f32_e32 v64, 0x42a00000, v62
	v_min_f32_e32 v65, 0x42a00000, v63
	v_exp_f32_e32 v62, v60
	v_exp_f32_e32 v63, v61
	v_exp_f32_e32 v84, v64
	v_exp_f32_e32 v85, v65
	v_add_f32_e32 v60, 1.0, v62
	v_add_f32_e32 v61, 1.0, v63
	v_add_f32_e32 v64, 1.0, v84
	v_add_f32_e32 v65, 1.0, v85
	v_rcp_f32_e32 v66, v60
	v_rcp_f32_e32 v67, v61
	v_rcp_f32_e32 v60, v64
	v_rcp_f32_e32 v61, v65
	v_pk_mul_f32 v[64:65], v[62:63], v[66:67]
	v_pk_mul_f32 v[62:63], v[84:85], v[60:61]
	s_cbranch_scc1 .LBB0_421
	v_mov_b32_e32 v84, v93
	s_nop 0
	v_cmp_lt_i32_e64 s[12:13], v129, v84
	v_cmp_lt_i32_e64 s[14:15], v130, v84
	v_cmp_lt_i32_e64 s[10:11], v128, v84
	s_or_b64 s[12:13], s[14:15], s[12:13]
	v_cmp_lt_i32_e32 vcc, v98, v84
	s_or_b64 s[10:11], s[12:13], s[10:11]
	s_or_b64 vcc, s[10:11], vcc
	v_cndmask_b32_e64 v63, 0, v63, s[14:15]
	v_cndmask_b32_e64 v62, 0, v62, s[12:13]
	v_cndmask_b32_e64 v65, 0, v65, s[10:11]
	v_cndmask_b32_e32 v64, 0, v64, vcc
	v_cndmask_b32_e64 v60, 1.0, v60, s[12:13]
	v_cndmask_b32_e64 v67, 1.0, v67, s[10:11]
	v_cndmask_b32_e32 v66, 1.0, v66, vcc
	v_cndmask_b32_e64 v61, 1.0, v61, s[14:15]

; #define LAS __attribute__((address_space(3)))
; __device__ __forceinline__ float fexp2(float x) { return __builtin_amdgcn_exp2f(x); }
; __device__ __forceinline__ float frcp(float x) { return __builtin_amdgcn_rcpf(x); }
; __device__ __forceinline__ f32x4 mfma16(bf16x8 a, bf16x8 b, f32x4 c) { return __builtin_amdgcn_mfma_f32_16x16x32_bf16(a, b, c, 0, 0, 0); }
; __device__ __forceinline__ void attn_unit(LAS unsigned char* lds, const bf16* P, bf16* Y, const float* gq, const float* gk, int b, int h, int qb, int tid, int wid, int lane, ...
;     ...
;                         const int st = 2 * p + u, sg = 8 * kt + st;
;                         if (sg > tg) {
; #pragma unroll
;                             for (int j = 0; j < 4; ++j) av[u][j] = 0.f;
;                         } else {
;                             const bf16x8 a0 = *(const LAS bf16x8*)(Ks + (16 * st + tq) * 72 + 8 * quad), a1 = *(const LAS bf16x8*)(Ks + (16 * st + tq) * 72 + 32 + 8 * quad);
;                             f32x4 z = (f32x4){0.f, 0.f, 0.f, 0.f};
;                             z = mfma16(a0, Bq0, z); z = mfma16(a1, Bq1, z);
;                             float r[4], be[4];
; #pragma unroll
;                             for (int j = 0; j < 4; ++j) { const float e = fexp2(fminf(z[j], 80.f)); const float rr = frcp(1.0f + e); r[j] = rr; be[j] = e * rr; }
;                             if (sg == tg) {
;                                 int tql = tq; asm volatile("" : "+v"(tql));
; #pragma unroll
;                                 for (int j = 0; j < 4; ++j) if (4 * quad + j >= tql) { r[j] = 1.0f; be[j] = 0.f; }
.LBB0_428:
	s_add_i32 s12, s82, 0x72
	s_cmp_gt_u32 s12, s36
	s_cselect_b64 s[12:13], -1, 0
	s_or_b64 s[12:13], s[12:13], s[10:11]
	s_and_b64 vcc, exec, s[12:13]
	s_cbranch_vccnz .LBB0_449
	s_add_i32 s10, s82, 0x73
	s_cmp_gt_u32 s10, s36
	v_mov_b32_e32 v59, 0
	s_cbranch_scc1 .LBB0_439
	ds_read_b128 v[56:59], v137
	ds_read_b128 v[60:63], v137 offset:64
	s_cmp_lg_u32 s40, s78
	s_waitcnt lgkmcnt(1)
	v_mfma_f32_16x16x32_bf16 v[56:59], v[56:59], v[24:27], 0
	s_waitcnt lgkmcnt(0)
	v_mfma_f32_16x16x32_bf16 v[56:59], v[60:63], v[28:31], v[56:59]
	s_nop 7
	v_min_f32_e32 v56, 0x42a00000, v56
	v_min_f32_e32 v57, 0x42a00000, v57
	v_min_f32_e32 v60, 0x42a00000, v58
	v_min_f32_e32 v61, 0x42a00000, v59
	v_exp_f32_e32 v58, v56
	v_exp_f32_e32 v59, v57
	v_exp_f32_e32 v60, v60
	v_exp_f32_e32 v61, v61
	v_add_f32_e32 v56, 1.0, v58
	v_add_f32_e32 v57, 1.0, v59
	v_add_f32_e32 v64, 1.0, v60
	v_add_f32_e32 v65, 1.0, v61
	v_rcp_f32_e32 v62, v56
	v_rcp_f32_e32 v63, v57
	v_rcp_f32_e32 v56, v64
	v_rcp_f32_e32 v57, v65
	v_pk_mul_f32 v[58:59], v[58:59], v[62:63]
	v_pk_mul_f32 v[60:61], v[60:61], v[56:57]
	s_cbranch_scc1 .LBB0_432
	v_mov_b32_e32 v64, v93
	s_nop 0
	v_cmp_lt_i32_e64 s[12:13], v129, v64
	v_cmp_lt_i32_e64 s[14:15], v130, v64
	v_cmp_lt_i32_e64 s[10:11], v128, v64
	s_or_b64 s[12:13], s[14:15], s[12:13]
	v_cmp_lt_i32_e32 vcc, v98, v64
	s_or_b64 s[10:11], s[12:13], s[10:11]
	s_or_b64 vcc, s[10:11], vcc
	v_cndmask_b32_e64 v61, 0, v61, s[14:15]
	v_cndmask_b32_e64 v60, 0, v60, s[12:13]
	v_cndmask_b32_e64 v59, 0, v59, s[10:11]
	v_cndmask_b32_e32 v58, 0, v58, vcc
	v_cndmask_b32_e64 v56, 1.0, v56, s[12:13]
	v_cndmask_b32_e64 v63, 1.0, v63, s[10:11]
	v_cndmask_b32_e32 v62, 1.0, v62, vcc
	v_cndmask_b32_e64 v57, 1.0, v57, s[14:15]

; #define LAS __attribute__((address_space(3)))
; __device__ __forceinline__ float fexp2(float x) { return __builtin_amdgcn_exp2f(x); }
; __device__ __forceinline__ float frcp(float x) { return __builtin_amdgcn_rcpf(x); }
; __device__ __forceinline__ f32x4 mfma16(bf16x8 a, bf16x8 b, f32x4 c) { return __builtin_amdgcn_mfma_f32_16x16x32_bf16(a, b, c, 0, 0, 0); }
; __device__ __forceinline__ void attn_unit(LAS unsigned char* lds, const bf16* P, bf16* Y, const float* gq, const float* gk, int b, int h, int qb, int tid, int wid, int lane, ...
;     ...
;                         const int st = 2 * p + u, sg = 8 * kt + st;
;                         if (sg > tg) {
; #pragma unroll
;                             for (int j = 0; j < 4; ++j) av[u][j] = 0.f;
;                         } else {
;                             const bf16x8 a0 = *(const LAS bf16x8*)(Ks + (16 * st + tq) * 72 + 8 * quad), a1 = *(const LAS bf16x8*)(Ks + (16 * st + tq) * 72 + 32 + 8 * quad);
;                             f32x4 z = (f32x4){0.f, 0.f, 0.f, 0.f};
;                             z = mfma16(a0, Bq0, z); z = mfma16(a1, Bq1, z);
;                             float r[4], be[4];
; #pragma unroll
;                             for (int j = 0; j < 4; ++j) { const float e = fexp2(fminf(z[j], 80.f)); const float rr = frcp(1.0f + e); r[j] = rr; be[j] = e * rr; }
;                             if (sg == tg) {
;                                 int tql = tq; asm volatile("" : "+v"(tql));
; #pragma unroll
;                                 for (int j = 0; j < 4; ++j) if (4 * quad + j >= tql) { r[j] = 1.0f; be[j] = 0.f; }
.LBB0_440:
	ds_read_b128 v[60:63], v138
	ds_read_b128 v[64:67], v138 offset:64
	s_cmp_lg_u32 s41, s78
	s_waitcnt lgkmcnt(1)
	v_mfma_f32_16x16x32_bf16 v[60:63], v[60:63], v[24:27], 0
	s_waitcnt lgkmcnt(0)
	v_mfma_f32_16x16x32_bf16 v[60:63], v[64:67], v[28:31], v[60:63]
	s_nop 7
	v_min_f32_e32 v60, 0x42a00000, v60
	v_min_f32_e32 v61, 0x42a00000, v61
	v_min_f32_e32 v64, 0x42a00000, v62
	v_min_f32_e32 v65, 0x42a00000, v63
	v_exp_f32_e32 v62, v60
	v_exp_f32_e32 v63, v61
	v_exp_f32_e32 v84, v64
	v_exp_f32_e32 v85, v65
	v_add_f32_e32 v60, 1.0, v62
	v_add_f32_e32 v61, 1.0, v63
	v_add_f32_e32 v64, 1.0, v84
	v_add_f32_e32 v65, 1.0, v85
	v_rcp_f32_e32 v66, v60
	v_rcp_f32_e32 v67, v61
	v_rcp_f32_e32 v60, v64
	v_rcp_f32_e32 v61, v65
	v_pk_mul_f32 v[64:65], v[62:63], v[66:67]
	v_pk_mul_f32 v[62:63], v[84:85], v[60:61]
	s_cbranch_scc1 .LBB0_442
	v_mov_b32_e32 v84, v93
	s_nop 0
	v_cmp_lt_i32_e64 s[12:13], v129, v84
	v_cmp_lt_i32_e64 s[14:15], v130, v84
	v_cmp_lt_i32_e64 s[10:11], v128, v84
	s_or_b64 s[12:13], s[14:15], s[12:13]
	v_cmp_lt_i32_e32 vcc, v98, v84
	s_or_b64 s[10:11], s[12:13], s[10:11]
	s_or_b64 vcc, s[10:11], vcc
	v_cndmask_b32_e64 v63, 0, v63, s[14:15]
	v_cndmask_b32_e64 v62, 0, v62, s[12:13]
	v_cndmask_b32_e64 v65, 0, v65, s[10:11]
	v_cndmask_b32_e32 v64, 0, v64, vcc
	v_cndmask_b32_e64 v60, 1.0, v60, s[12:13]
	v_cndmask_b32_e64 v67, 1.0, v67, s[10:11]
	v_cndmask_b32_e32 v66, 1.0, v66, vcc
	v_cndmask_b32_e64 v61, 1.0, v61, s[14:15]

; #define LAS __attribute__((address_space(3)))
; __device__ __forceinline__ float fexp2(float x) { return __builtin_amdgcn_exp2f(x); }
; __device__ __forceinline__ float frcp(float x) { return __builtin_amdgcn_rcpf(x); }
; __device__ __forceinline__ f32x4 mfma16(bf16x8 a, bf16x8 b, f32x4 c) { return __builtin_amdgcn_mfma_f32_16x16x32_bf16(a, b, c, 0, 0, 0); }
; __device__ __forceinline__ void attn_unit(LAS unsigned char* lds, const bf16* P, bf16* Y, const float* gq, const float* gk, int b, int h, int qb, int tid, int wid, int lane, ...
;     ...
;                         const int st = 2 * p + u, sg = 8 * kt + st;
;                         if (sg > tg) {
; #pragma unroll
;                             for (int j = 0; j < 4; ++j) av[u][j] = 0.f;
;                         } else {
;                             const bf16x8 a0 = *(const LAS bf16x8*)(Ks + (16 * st + tq) * 72 + 8 * quad), a1 = *(const LAS bf16x8*)(Ks + (16 * st + tq) * 72 + 32 + 8 * quad);
;                             f32x4 z = (f32x4){0.f, 0.f, 0.f, 0.f};
;                             z = mfma16(a0, Bq0, z); z = mfma16(a1, Bq1, z);
;                             float r[4], be[4];
; #pragma unroll
;                             for (int j = 0; j < 4; ++j) { const float e = fexp2(fminf(z[j], 80.f)); const float rr = frcp(1.0f + e); r[j] = rr; be[j] = e * rr; }
;                             if (sg == tg) {
;                                 int tql = tq; asm volatile("" : "+v"(tql));
; #pragma unroll
;                                 for (int j = 0; j < 4; ++j) if (4 * quad + j >= tql) { r[j] = 1.0f; be[j] = 0.f; }
.LBB0_449:
	s_addk_i32 s82, 0x70
	s_cmp_gt_u32 s82, s36
	s_cselect_b64 s[12:13], -1, 0
	s_or_b64 s[12:13], s[12:13], s[10:11]
	s_and_b64 vcc, exec, s[12:13]
	s_cbranch_vccnz .LBB0_470
	s_cmp_ge_u32 s82, s36
	v_mov_b32_e32 v59, 0
	s_cbranch_scc1 .LBB0_460
	ds_read_b128 v[56:59], v136 offset:2304
	ds_read_b128 v[60:63], v136 offset:2368
	s_cmp_lg_u32 s3, s78
	s_waitcnt lgkmcnt(1)
	v_mfma_f32_16x16x32_bf16 v[56:59], v[56:59], v[24:27], 0
	s_waitcnt lgkmcnt(0)
	v_mfma_f32_16x16x32_bf16 v[56:59], v[60:63], v[28:31], v[56:59]
	s_nop 7
	v_min_f32_e32 v56, 0x42a00000, v56
	v_min_f32_e32 v57, 0x42a00000, v57
	v_min_f32_e32 v60, 0x42a00000, v58
	v_min_f32_e32 v61, 0x42a00000, v59
	v_exp_f32_e32 v58, v56
	v_exp_f32_e32 v59, v57
	v_exp_f32_e32 v60, v60
	v_exp_f32_e32 v61, v61
	v_add_f32_e32 v56, 1.0, v58
	v_add_f32_e32 v57, 1.0, v59
	v_add_f32_e32 v64, 1.0, v60
	v_add_f32_e32 v65, 1.0, v61
	v_rcp_f32_e32 v62, v56
	v_rcp_f32_e32 v63, v57
	v_rcp_f32_e32 v56, v64
	v_rcp_f32_e32 v57, v65
	v_pk_mul_f32 v[58:59], v[58:59], v[62:63]
	v_pk_mul_f32 v[60:61], v[60:61], v[56:57]
	s_cbranch_scc1 .LBB0_453
	v_mov_b32_e32 v64, v93
	s_nop 0
	v_cmp_lt_i32_e64 s[12:13], v129, v64
	v_cmp_lt_i32_e64 s[14:15], v130, v64
	v_cmp_lt_i32_e64 s[10:11], v128, v64
	s_or_b64 s[12:13], s[14:15], s[12:13]
	v_cmp_lt_i32_e32 vcc, v98, v64
	s_or_b64 s[10:11], s[12:13], s[10:11]
	s_or_b64 vcc, s[10:11], vcc
	v_cndmask_b32_e64 v61, 0, v61, s[14:15]
	v_cndmask_b32_e64 v60, 0, v60, s[12:13]
	v_cndmask_b32_e64 v59, 0, v59, s[10:11]
	v_cndmask_b32_e32 v58, 0, v58, vcc
	v_cndmask_b32_e64 v56, 1.0, v56, s[12:13]
	v_cndmask_b32_e64 v63, 1.0, v63, s[10:11]
	v_cndmask_b32_e32 v62, 1.0, v62, vcc
	v_cndmask_b32_e64 v57, 1.0, v57, s[14:15]

; #define LAS __attribute__((address_space(3)))
; __device__ __forceinline__ float fexp2(float x) { return __builtin_amdgcn_exp2f(x); }
; __device__ __forceinline__ float frcp(float x) { return __builtin_amdgcn_rcpf(x); }
; __device__ __forceinline__ f32x4 mfma16(bf16x8 a, bf16x8 b, f32x4 c) { return __builtin_amdgcn_mfma_f32_16x16x32_bf16(a, b, c, 0, 0, 0); }
; __device__ __forceinline__ void attn_unit(LAS unsigned char* lds, const bf16* P, bf16* Y, const float* gq, const float* gk, int b, int h, int qb, int tid, int wid, int lane, ...
;     ...
;                         const int st = 2 * p + u, sg = 8 * kt + st;
;                         if (sg > tg) {
; #pragma unroll
;                             for (int j = 0; j < 4; ++j) av[u][j] = 0.f;
;                         } else {
;                             const bf16x8 a0 = *(const LAS bf16x8*)(Ks + (16 * st + tq) * 72 + 8 * quad), a1 = *(const LAS bf16x8*)(Ks + (16 * st + tq) * 72 + 32 + 8 * quad);
;                             f32x4 z = (f32x4){0.f, 0.f, 0.f, 0.f};
;                             z = mfma16(a0, Bq0, z); z = mfma16(a1, Bq1, z);
;                             float r[4], be[4];
; #pragma unroll
;                             for (int j = 0; j < 4; ++j) { const float e = fexp2(fminf(z[j], 80.f)); const float rr = frcp(1.0f + e); r[j] = rr; be[j] = e * rr; }
;                             if (sg == tg) {
;                                 int tql = tq; asm volatile("" : "+v"(tql));
; #pragma unroll
;                                 for (int j = 0; j < 4; ++j) if (4 * quad + j >= tql) { r[j] = 1.0f; be[j] = 0.f; }
.LBB0_461:
	ds_read_b128 v[60:63], v136
	ds_read_b128 v[64:67], v136 offset:64
	s_cmp_lg_u32 s33, s78
	s_waitcnt lgkmcnt(1)
	v_mfma_f32_16x16x32_bf16 v[60:63], v[60:63], v[24:27], 0
	s_waitcnt lgkmcnt(0)
	v_mfma_f32_16x16x32_bf16 v[60:63], v[64:67], v[28:31], v[60:63]
	s_nop 7
	v_min_f32_e32 v60, 0x42a00000, v60
	v_min_f32_e32 v61, 0x42a00000, v61
	v_min_f32_e32 v64, 0x42a00000, v62
	v_min_f32_e32 v65, 0x42a00000, v63
	v_exp_f32_e32 v62, v60
	v_exp_f32_e32 v63, v61
	v_exp_f32_e32 v84, v64
	v_exp_f32_e32 v85, v65
	v_add_f32_e32 v60, 1.0, v62
	v_add_f32_e32 v61, 1.0, v63
	v_add_f32_e32 v64, 1.0, v84
	v_add_f32_e32 v65, 1.0, v85
	v_rcp_f32_e32 v66, v60
	v_rcp_f32_e32 v67, v61
	v_rcp_f32_e32 v60, v64
	v_rcp_f32_e32 v61, v65
	v_pk_mul_f32 v[64:65], v[62:63], v[66:67]
	v_pk_mul_f32 v[62:63], v[84:85], v[60:61]
	s_cbranch_scc1 .LBB0_463
	v_mov_b32_e32 v84, v93
	s_nop 0
	v_cmp_lt_i32_e64 s[12:13], v129, v84
	v_cmp_lt_i32_e64 s[14:15], v130, v84
	v_cmp_lt_i32_e64 s[10:11], v128, v84
	s_or_b64 s[12:13], s[14:15], s[12:13]
	v_cmp_lt_i32_e32 vcc, v98, v84
	s_or_b64 s[10:11], s[12:13], s[10:11]
	s_or_b64 vcc, s[10:11], vcc
	v_cndmask_b32_e64 v63, 0, v63, s[14:15]
	v_cndmask_b32_e64 v62, 0, v62, s[12:13]
	v_cndmask_b32_e64 v65, 0, v65, s[10:11]
	v_cndmask_b32_e32 v64, 0, v64, vcc
	v_cndmask_b32_e64 v60, 1.0, v60, s[12:13]
	v_cndmask_b32_e64 v67, 1.0, v67, s[10:11]
	v_cndmask_b32_e32 v66, 1.0, v66, vcc
	v_cndmask_b32_e64 v61, 1.0, v61, s[14:15]

; #define LAS __attribute__((address_space(3)))
; __device__ __forceinline__ void attn_unit(LAS unsigned char* lds, const bf16* P, bf16* Y, const float* gq, const float* gk, int b, int h, int qb, int tid, int wid, int lane, ...
;     ...
;                 float kf[8];
; #pragma unroll
;                 for (int i = 0; i < 4; ++i) { kf[2 * i] = blo(kw[hf][i]); kf[2 * i + 1] = bhi(kw[hf][i]); }
;                 float ss = 0.f;
; #pragma unroll
;                 for (int i = 0; i < 8; ++i) ss += kf[i] * kf[i];
;                 ss += __shfl_xor(ss, 1); ss += __shfl_xor(ss, 2); ss += __shfl_xor(ss, 4);
;                 const float rs = __builtin_amdgcn_rsqf(ss * (1.0f / 64.0f) + EPSN);
; #pragma unroll
;                 for (int i = 0; i < 4; ++i) { kf[i] *= rs * gk0[i]; kf[4 + i] *= rs * gk1[i]; }
;                 v4u o; o.x = pk2(kf[0], kf[1]); o.y = pk2(kf[2], kf[3]); o.z = pk2(kf[4], kf[5]); o.w = pk2(kf[6], kf[7]);
;                 *(LAS v4u*)(Ks + (sr + 64 * hf) * 72 + 8 * dc) = o;
; #pragma unroll
;                 for (int i = 0; i < 4; ++i) { Vt[(8 * (dcv + 4 * hf) + 2 * i) * 136 + srv] = (bf16)(vw[hf][i] & 0xffffu); Vt[(8 * (dcv + 4 * hf) + 2 * i + 1) * 136 + srv] = (bf16)(vw[hf][i] >> 16); }
;             }
;         }
;         if (tid == 0) flags[(it + 1) % 3] = 0;
;         LBAR();
;         if (!wdone) {
; #pragma unroll
;             for (int p = 3; p >= 0; --p) {
;                 if (8 * kt + 2 * p <= tg && !wdone) {
;                     float av[2][4];
; #pragma unroll
;                     for (int u = 1; u >= 0; --u) {
;                         const int st = 2 * p + u, sg = 8 * kt + st;
;                         if (sg > tg) {
; #pragma unroll
;                             for (int j = 0; j < 4; ++j) av[u][j] = 0.f;
;                         } else {
;                             const bf16x8 a0 = *(const LAS bf16x8*)(Ks + (16 * st + tq) * 72 + 8 * quad), a1 = *(const LAS bf16x8*)(Ks + (16 * st + tq) * 72 + 32 + 8 * quad);
;                             f32x4 z = (f32x4){0.f, 0.f, 0.f, 0.f};
;                             z = mfma16(a0, Bq0, z); z = mfma16(a1, Bq1, z);
;                             float r[4], be[4];
; #pragma unroll
;                             for (int j = 0; j < 4; ++j) { const float e = fexp2(fminf(z[j], 80.f)); const float rr = frcp(1.0f + e); r[j] = rr; be[j] = e * rr; }
;                             if (sg == tg) {
.LBB0_853:
	v_and_b32_e32 v70, 0xffff0000, v52
	v_lshlrev_b32_e32 v69, 16, v52
	v_mul_f32_e32 v75, v70, v70
	v_lshlrev_b32_e32 v71, 16, v53
	v_fmac_f32_e32 v75, v69, v69
	v_and_b32_e32 v72, 0xffff0000, v53
	v_fmac_f32_e32 v75, v71, v71
	v_lshlrev_b32_e32 v73, 16, v54
	v_fmac_f32_e32 v75, v72, v72
	v_and_b32_e32 v74, 0xffff0000, v54
	v_fmac_f32_e32 v75, v73, v73
	v_and_b32_e32 v52, 0xffff0000, v55
	v_lshlrev_b32_e32 v53, 16, v55
	v_fmac_f32_e32 v75, v74, v74
	v_pk_mul_f32 v[54:55], v[52:53], v[52:53]
	v_lshlrev_b32_e32 v80, 16, v50
	v_add_f32_e32 v55, v55, v75
	v_add_f32_e32 v54, v54, v55
	ds_bpermute_b32 v55, v126, v54
	v_and_b32_e32 v81, 0xffff0000, v50
	v_and_b32_e32 v79, 0xffff0000, v49
	s_waitcnt lgkmcnt(0)
	v_add_f32_e32 v54, v54, v55
	ds_bpermute_b32 v55, v127, v54
	s_waitcnt lgkmcnt(0)
	v_add_f32_e32 v54, v54, v55
	ds_bpermute_b32 v55, v128, v54
	s_waitcnt lgkmcnt(0)
	v_add_f32_e32 v54, v54, v55
	v_fmamk_f32 v54, v54, 0x3c800000, v142
	v_rsq_f32_e32 v75, v54
	s_waitcnt vmcnt(1)
	v_mul_f32_e32 v77, v33, v75
	s_waitcnt vmcnt(0)
	v_mul_f32_e32 v76, v37, v75
	v_mul_f32_e32 v74, v77, v74
	v_and_b32_e32 v77, 0xffff0000, v48
	v_mul_f32_e32 v78, v38, v75
	v_mul_f32_e32 v70, v76, v70
	v_lshlrev_b32_e32 v76, 16, v48
	v_mul_f32_e32 v50, v77, v77
	v_mul_f32_e32 v54, v36, v75
	v_mul_f32_e32 v71, v78, v71
	v_lshlrev_b32_e32 v78, 16, v49
	v_fmac_f32_e32 v50, v76, v76
	v_mul_f32_e32 v69, v54, v69
	v_mul_f32_e32 v54, v34, v75
	v_fmac_f32_e32 v50, v78, v78
	v_mul_f32_e32 v55, v32, v75
	v_mul_f32_e32 v53, v54, v53
	v_mul_f32_e32 v54, v39, v75
	v_fmac_f32_e32 v50, v79, v79
	v_mul_f32_e32 v73, v55, v73
	v_mul_f32_e32 v72, v54, v72
	v_fmac_f32_e32 v50, v80, v80
	v_and_b32_e32 v54, 0xffff0000, v51
	v_lshlrev_b32_e32 v55, 16, v51
	v_fmac_f32_e32 v50, v81, v81
	v_pk_mul_f32 v[48:49], v[54:55], v[54:55]
	s_nop 0
	v_add_f32_e32 v49, v49, v50
	v_add_f32_e32 v50, v48, v49
	ds_bpermute_b32 v51, v126, v50
	v_mul_f32_e32 v48, v35, v75
	v_mul_f32_e32 v52, v48, v52
	v_cvt_pk_bf16_f32 v48, v69, v70
	v_cvt_pk_bf16_f32 v49, v71, v72
	s_waitcnt lgkmcnt(0)
	v_add_f32_e32 v69, v50, v51
	ds_bpermute_b32 v70, v127, v69
	v_cvt_pk_bf16_f32 v50, v73, v74
	v_cvt_pk_bf16_f32 v51, v53, v52
	ds_write_b128 v145, v[48:51]
	ds_write_b16 v129, v44 offset:18432
	ds_write_b16_d16_hi v129, v44 offset:18704
	ds_write_b16 v129, v45 offset:18976
	ds_write_b16_d16_hi v129, v45 offset:19248
	ds_write_b16 v129, v46 offset:19520
	s_waitcnt lgkmcnt(6)
	v_add_f32_e32 v48, v69, v70
	ds_bpermute_b32 v49, v128, v48
	ds_write_b16_d16_hi v129, v46 offset:19792
	ds_write_b16 v129, v47 offset:20064
	ds_write_b16_d16_hi v129, v47 offset:20336
	s_waitcnt lgkmcnt(3)
	v_add_f32_e32 v44, v48, v49
	v_fmamk_f32 v44, v44, 0x3c800000, v142
	v_rsq_f32_e32 v44, v44
	s_nop 0
	v_mul_f32_e32 v45, v36, v44
	v_mul_f32_e32 v46, v32, v44
	v_mul_f32_e32 v47, v37, v44
	v_mul_f32_e32 v45, v45, v76
	v_mul_f32_e32 v46, v46, v80
	v_mul_f32_e32 v47, v47, v77
	v_mul_f32_e32 v48, v33, v44
	v_mul_f32_e32 v49, v38, v44
	v_mul_f32_e32 v50, v34, v44
	v_mul_f32_e32 v51, v39, v44
	v_mul_f32_e32 v44, v35, v44
	v_mul_f32_e32 v48, v48, v81
	v_mul_f32_e32 v49, v49, v78
	v_mul_f32_e32 v50, v50, v55
	v_mul_f32_e32 v51, v51, v79
	v_mul_f32_e32 v52, v44, v54
	v_cvt_pk_bf16_f32 v44, v45, v47
	v_cvt_pk_bf16_f32 v45, v49, v51
	v_cvt_pk_bf16_f32 v46, v46, v48
	v_cvt_pk_bf16_f32 v47, v50, v52
	ds_write_b128 v145, v[44:47] offset:9216
	ds_write_b16 v129, v40 offset:27136
	ds_write_b16_d16_hi v129, v40 offset:27408
	ds_write_b16 v129, v41 offset:27680
	ds_write_b16_d16_hi v129, v41 offset:27952
	ds_write_b16 v129, v42 offset:28224
	ds_write_b16_d16_hi v129, v42 offset:28496
	ds_write_b16 v129, v43 offset:28768
	ds_write_b16_d16_hi v129, v43 offset:29040
	s_mov_b64 s[10:11], exec
	v_readlane_b32 s12, v249, 8
	v_readlane_b32 s13, v249, 9
	s_and_b64 s[12:13], s[10:11], s[12:13]
	s_mov_b64 exec, s[12:13]
	ds_write_b32 v95, v95 offset:35844
	s_or_b64 exec, exec, s[10:11]
	s_waitcnt lgkmcnt(0)
	s_barrier
	s_andn2_b64 vcc, exec, s[0:1]
	s_cbranch_vccnz .LBB0_866
	s_andn2_b64 vcc, exec, s[18:19]
	s_cbranch_vccnz .LBB0_867
	ds_read_b128 v[40:43], v137
	ds_read_b128 v[44:47], v137 offset:64
	s_andn2_b64 vcc, exec, s[20:21]
	s_waitcnt lgkmcnt(1)
	v_mfma_f32_16x16x32_bf16 v[40:43], v[40:43], v[24:27], 0
	s_waitcnt lgkmcnt(0)
	v_mfma_f32_16x16x32_bf16 v[40:43], v[44:47], v[28:31], v[40:43]
	s_nop 7
	v_min_f32_e32 v40, 0x42a00000, v40
	v_min_f32_e32 v41, 0x42a00000, v41
	v_min_f32_e32 v42, 0x42a00000, v42
	v_min_f32_e32 v43, 0x42a00000, v43
	v_exp_f32_e32 v40, v40
	v_exp_f32_e32 v41, v41
	v_exp_f32_e32 v46, v42
	v_exp_f32_e32 v47, v43
	v_add_f32_e32 v42, 1.0, v40
	v_add_f32_e32 v43, 1.0, v41
	v_add_f32_e32 v44, 1.0, v46
	v_add_f32_e32 v45, 1.0, v47
	v_rcp_f32_e32 v48, v42
	v_rcp_f32_e32 v49, v43
	v_rcp_f32_e32 v44, v44
	v_rcp_f32_e32 v45, v45
	v_pk_mul_f32 v[42:43], v[40:41], v[48:49]
	v_pk_mul_f32 v[40:41], v[46:47], v[44:45]
	s_cbranch_vccnz .LBB0_859
	v_mov_b32_e32 v46, v91
	s_nop 0
	v_cmp_lt_i32_e64 s[12:13], v131, v46
	v_cmp_lt_i32_e64 s[14:15], v132, v46
	v_cmp_lt_i32_e64 s[10:11], v130, v46
	s_or_b64 s[12:13], s[14:15], s[12:13]
	v_cmp_lt_i32_e32 vcc, v98, v46
	s_or_b64 s[10:11], s[12:13], s[10:11]
	s_or_b64 vcc, s[10:11], vcc
	v_cndmask_b32_e64 v41, 0, v41, s[14:15]
	v_cndmask_b32_e64 v40, 0, v40, s[12:13]
	v_cndmask_b32_e64 v43, 0, v43, s[10:11]
	v_cndmask_b32_e32 v42, 0, v42, vcc
	v_cndmask_b32_e64 v44, 1.0, v44, s[12:13]
	v_cndmask_b32_e64 v49, 1.0, v49, s[10:11]
	v_cndmask_b32_e32 v48, 1.0, v48, vcc
	v_cndmask_b32_e64 v45, 1.0, v45, s[14:15]

; #define LAS __attribute__((address_space(3)))
; __device__ __forceinline__ float fexp2(float x) { return __builtin_amdgcn_exp2f(x); }
; __device__ __forceinline__ float frcp(float x) { return __builtin_amdgcn_rcpf(x); }
; __device__ __forceinline__ f32x4 mfma16(bf16x8 a, bf16x8 b, f32x4 c) { return __builtin_amdgcn_mfma_f32_16x16x32_bf16(a, b, c, 0, 0, 0); }
; __device__ __forceinline__ void attn_unit(LAS unsigned char* lds, const bf16* P, bf16* Y, const float* gq, const float* gk, int b, int h, int qb, int tid, int wid, int lane, ...
;     ...
;                             const bf16x8 a0 = *(const LAS bf16x8*)(Ks + (16 * st + tq) * 72 + 8 * quad), a1 = *(const LAS bf16x8*)(Ks + (16 * st + tq) * 72 + 32 + 8 * quad);
;                             f32x4 z = (f32x4){0.f, 0.f, 0.f, 0.f};
;                             z = mfma16(a0, Bq0, z); z = mfma16(a1, Bq1, z);
;                             float r[4], be[4];
; #pragma unroll
;                             for (int j = 0; j < 4; ++j) { const float e = fexp2(fminf(z[j], 80.f)); const float rr = frcp(1.0f + e); r[j] = rr; be[j] = e * rr; }
;                             if (sg == tg) {
;                                 int tql = tq; asm volatile("" : "+v"(tql));
; #pragma unroll
;                                 for (int j = 0; j < 4; ++j) if (4 * quad + j >= tql) { r[j] = 1.0f; be[j] = 0.f; }
.LBB0_868:
	ds_read_b128 v[44:47], v138 offset:13824
	ds_read_b128 v[48:51], v138 offset:13888
	s_andn2_b64 vcc, exec, s[16:17]
	s_waitcnt lgkmcnt(1)
	v_mfma_f32_16x16x32_bf16 v[44:47], v[44:47], v[24:27], 0
	s_waitcnt lgkmcnt(0)
	v_mfma_f32_16x16x32_bf16 v[44:47], v[48:51], v[28:31], v[44:47]
	s_nop 7
	v_min_f32_e32 v44, 0x42a00000, v44
	v_min_f32_e32 v45, 0x42a00000, v45
	v_min_f32_e32 v48, 0x42a00000, v46
	v_min_f32_e32 v49, 0x42a00000, v47
	v_exp_f32_e32 v46, v44
	v_exp_f32_e32 v47, v45
	v_exp_f32_e32 v52, v48
	v_exp_f32_e32 v53, v49
	v_add_f32_e32 v44, 1.0, v46
	v_add_f32_e32 v45, 1.0, v47
	v_add_f32_e32 v48, 1.0, v52
	v_add_f32_e32 v49, 1.0, v53
	v_rcp_f32_e32 v50, v44
	v_rcp_f32_e32 v51, v45
	v_rcp_f32_e32 v44, v48
	v_rcp_f32_e32 v45, v49
	v_pk_mul_f32 v[48:49], v[46:47], v[50:51]
	v_pk_mul_f32 v[46:47], v[52:53], v[44:45]
	s_cbranch_vccnz .LBB0_870
	v_mov_b32_e32 v52, v91
	s_nop 0
	v_cmp_lt_i32_e64 s[12:13], v131, v52
	v_cmp_lt_i32_e64 s[14:15], v132, v52
	v_cmp_lt_i32_e64 s[10:11], v130, v52
	s_or_b64 s[12:13], s[14:15], s[12:13]
	v_cmp_lt_i32_e32 vcc, v98, v52
	s_or_b64 s[10:11], s[12:13], s[10:11]
	s_or_b64 vcc, s[10:11], vcc
	v_cndmask_b32_e64 v47, 0, v47, s[14:15]
	v_cndmask_b32_e64 v46, 0, v46, s[12:13]
	v_cndmask_b32_e64 v49, 0, v49, s[10:11]
	v_cndmask_b32_e32 v48, 0, v48, vcc
	v_cndmask_b32_e64 v44, 1.0, v44, s[12:13]
	v_cndmask_b32_e64 v51, 1.0, v51, s[10:11]
	v_cndmask_b32_e32 v50, 1.0, v50, vcc
	v_cndmask_b32_e64 v45, 1.0, v45, s[14:15]

; #define LAS __attribute__((address_space(3)))
; __device__ __forceinline__ float fexp2(float x) { return __builtin_amdgcn_exp2f(x); }
; __device__ __forceinline__ float frcp(float x) { return __builtin_amdgcn_rcpf(x); }
; __device__ __forceinline__ f32x4 mfma16(bf16x8 a, bf16x8 b, f32x4 c) { return __builtin_amdgcn_mfma_f32_16x16x32_bf16(a, b, c, 0, 0, 0); }
; #define LBAR() do { asm volatile("s_waitcnt lgkmcnt(0)" ::: "memory"); __builtin_amdgcn_s_barrier(); asm volatile("" ::: "memory"); } while (0)
; __device__ __forceinline__ void attn_unit(LAS unsigned char* lds, const bf16* P, bf16* Y, const float* gq, const float* gk, int b, int h, int qb, int tid, int wid, int lane, ...
;     ...
;         if (tid == 0) flags[(it + 1) % 3] = 0;
;         LBAR();
;         if (!wdone) {
; #pragma unroll
;             for (int p = 3; p >= 0; --p) {
;                 if (8 * kt + 2 * p <= tg && !wdone) {
;                     float av[2][4];
; #pragma unroll
;                     for (int u = 1; u >= 0; --u) {
;                         const int st = 2 * p + u, sg = 8 * kt + st;
;                         if (sg > tg) {
; #pragma unroll
;                             for (int j = 0; j < 4; ++j) av[u][j] = 0.f;
;                         } else {
;                             const bf16x8 a0 = *(const LAS bf16x8*)(Ks + (16 * st + tq) * 72 + 8 * quad), a1 = *(const LAS bf16x8*)(Ks + (16 * st + tq) * 72 + 32 + 8 * quad);
;                             f32x4 z = (f32x4){0.f, 0.f, 0.f, 0.f};
;                             z = mfma16(a0, Bq0, z); z = mfma16(a1, Bq1, z);
;                             float r[4], be[4];
; #pragma unroll
;                             for (int j = 0; j < 4; ++j) { const float e = fexp2(fminf(z[j], 80.f)); const float rr = frcp(1.0f + e); r[j] = rr; be[j] = e * rr; }
;                             if (sg == tg) {
;                                 int tql = tq; asm volatile("" : "+v"(tql));
; #pragma unroll
;                                 for (int j = 0; j < 4; ++j) if (4 * quad + j >= tql) { r[j] = 1.0f; be[j] = 0.f; }
.LBB0_909:
	s_or_b64 exec, exec, s[12:13]
	s_xor_b64 s[12:13], s[10:11], -1
	s_mul_hi_u32 s10, s73, 0xaaaaaaab
	s_waitcnt lgkmcnt(0)
	s_barrier
	s_lshr_b32 s79, s10, 1
	s_mul_i32 s79, s79, -12
	s_mov_b64 s[10:11], -1
	s_and_saveexec_b64 s[64:65], s[12:13]
	s_cbranch_execz .LBB0_997
	s_add_i32 s80, s72, s76
	s_add_i32 s10, s80, 0x76
	s_cmp_gt_u32 s10, s41
	s_mov_b64 s[10:11], 0
	s_cbranch_scc1 .LBB0_931
	s_add_i32 s10, s80, 0x77
	s_cmp_gt_u32 s10, s41
	v_mov_b32_e32 v59, 0
	s_cbranch_scc1 .LBB0_921
	ds_read_b128 v[56:59], v137
	ds_read_b128 v[60:63], v137 offset:64
	s_cmp_lg_u32 s52, s76
	s_waitcnt lgkmcnt(1)
	v_mfma_f32_16x16x32_bf16 v[56:59], v[56:59], v[24:27], 0
	s_waitcnt lgkmcnt(0)
	v_mfma_f32_16x16x32_bf16 v[56:59], v[60:63], v[28:31], v[56:59]
	s_nop 7
	v_min_f32_e32 v56, 0x42a00000, v56
	v_min_f32_e32 v57, 0x42a00000, v57
	v_min_f32_e32 v60, 0x42a00000, v58
	v_min_f32_e32 v61, 0x42a00000, v59
	v_exp_f32_e32 v58, v56
	v_exp_f32_e32 v59, v57
	v_exp_f32_e32 v60, v60
	v_exp_f32_e32 v61, v61
	v_add_f32_e32 v56, 1.0, v58
	v_add_f32_e32 v57, 1.0, v59
	v_add_f32_e32 v64, 1.0, v60
	v_add_f32_e32 v65, 1.0, v61
	v_rcp_f32_e32 v62, v56
	v_rcp_f32_e32 v63, v57
	v_rcp_f32_e32 v56, v64
	v_rcp_f32_e32 v57, v65
	v_pk_mul_f32 v[58:59], v[58:59], v[62:63]
	v_pk_mul_f32 v[60:61], v[60:61], v[56:57]
	s_cbranch_scc1 .LBB0_914
	v_mov_b32_e32 v64, v91
	s_nop 0
	v_cmp_lt_i32_e64 s[12:13], v131, v64
	v_cmp_lt_i32_e64 s[14:15], v132, v64
	v_cmp_lt_i32_e64 s[10:11], v130, v64
	s_or_b64 s[12:13], s[14:15], s[12:13]
	v_cmp_lt_i32_e32 vcc, v98, v64
	s_or_b64 s[10:11], s[12:13], s[10:11]
	s_or_b64 vcc, s[10:11], vcc
	v_cndmask_b32_e64 v61, 0, v61, s[14:15]
	v_cndmask_b32_e64 v60, 0, v60, s[12:13]
	v_cndmask_b32_e64 v59, 0, v59, s[10:11]
	v_cndmask_b32_e32 v58, 0, v58, vcc
	v_cndmask_b32_e64 v56, 1.0, v56, s[12:13]
	v_cndmask_b32_e64 v63, 1.0, v63, s[10:11]
	v_cndmask_b32_e32 v62, 1.0, v62, vcc
	v_cndmask_b32_e64 v57, 1.0, v57, s[14:15]

; #define LAS __attribute__((address_space(3)))
; __device__ __forceinline__ float fexp2(float x) { return __builtin_amdgcn_exp2f(x); }
; __device__ __forceinline__ float frcp(float x) { return __builtin_amdgcn_rcpf(x); }
; __device__ __forceinline__ f32x4 mfma16(bf16x8 a, bf16x8 b, f32x4 c) { return __builtin_amdgcn_mfma_f32_16x16x32_bf16(a, b, c, 0, 0, 0); }
; __device__ __forceinline__ void attn_unit(LAS unsigned char* lds, const bf16* P, bf16* Y, const float* gq, const float* gk, int b, int h, int qb, int tid, int wid, int lane, ...
;     ...
;                         const int st = 2 * p + u, sg = 8 * kt + st;
;                         if (sg > tg) {
; #pragma unroll
;                             for (int j = 0; j < 4; ++j) av[u][j] = 0.f;
;                         } else {
;                             const bf16x8 a0 = *(const LAS bf16x8*)(Ks + (16 * st + tq) * 72 + 8 * quad), a1 = *(const LAS bf16x8*)(Ks + (16 * st + tq) * 72 + 32 + 8 * quad);
;                             f32x4 z = (f32x4){0.f, 0.f, 0.f, 0.f};
;                             z = mfma16(a0, Bq0, z); z = mfma16(a1, Bq1, z);
;                             float r[4], be[4];
; #pragma unroll
;                             for (int j = 0; j < 4; ++j) { const float e = fexp2(fminf(z[j], 80.f)); const float rr = frcp(1.0f + e); r[j] = rr; be[j] = e * rr; }
;                             if (sg == tg) {
;                                 int tql = tq; asm volatile("" : "+v"(tql));
; #pragma unroll
;                                 for (int j = 0; j < 4; ++j) if (4 * quad + j >= tql) { r[j] = 1.0f; be[j] = 0.f; }
.LBB0_922:
	ds_read_b128 v[60:63], v138 offset:13824
	ds_read_b128 v[64:67], v138 offset:13888
	s_cmp_lg_u32 s53, s76
	s_waitcnt lgkmcnt(1)
	v_mfma_f32_16x16x32_bf16 v[60:63], v[60:63], v[24:27], 0
	s_waitcnt lgkmcnt(0)
	v_mfma_f32_16x16x32_bf16 v[60:63], v[64:67], v[28:31], v[60:63]
	s_nop 7
	v_min_f32_e32 v60, 0x42a00000, v60
	v_min_f32_e32 v61, 0x42a00000, v61
	v_min_f32_e32 v64, 0x42a00000, v62
	v_min_f32_e32 v65, 0x42a00000, v63
	v_exp_f32_e32 v62, v60
	v_exp_f32_e32 v63, v61
	v_exp_f32_e32 v84, v64
	v_exp_f32_e32 v85, v65
	v_add_f32_e32 v60, 1.0, v62
	v_add_f32_e32 v61, 1.0, v63
	v_add_f32_e32 v64, 1.0, v84
	v_add_f32_e32 v65, 1.0, v85
	v_rcp_f32_e32 v66, v60
	v_rcp_f32_e32 v67, v61
	v_rcp_f32_e32 v60, v64
	v_rcp_f32_e32 v61, v65
	v_pk_mul_f32 v[64:65], v[62:63], v[66:67]
	v_pk_mul_f32 v[62:63], v[84:85], v[60:61]
	s_cbranch_scc1 .LBB0_924
	v_mov_b32_e32 v84, v91
	s_nop 0
	v_cmp_lt_i32_e64 s[12:13], v131, v84
	v_cmp_lt_i32_e64 s[14:15], v132, v84
	v_cmp_lt_i32_e64 s[10:11], v130, v84
	s_or_b64 s[12:13], s[14:15], s[12:13]
	v_cmp_lt_i32_e32 vcc, v98, v84
	s_or_b64 s[10:11], s[12:13], s[10:11]
	s_or_b64 vcc, s[10:11], vcc
	v_cndmask_b32_e64 v63, 0, v63, s[14:15]
	v_cndmask_b32_e64 v62, 0, v62, s[12:13]
	v_cndmask_b32_e64 v65, 0, v65, s[10:11]
	v_cndmask_b32_e32 v64, 0, v64, vcc
	v_cndmask_b32_e64 v60, 1.0, v60, s[12:13]
	v_cndmask_b32_e64 v67, 1.0, v67, s[10:11]
	v_cndmask_b32_e32 v66, 1.0, v66, vcc
	v_cndmask_b32_e64 v61, 1.0, v61, s[14:15]

; #define LAS __attribute__((address_space(3)))
; __device__ __forceinline__ float fexp2(float x) { return __builtin_amdgcn_exp2f(x); }
; __device__ __forceinline__ float frcp(float x) { return __builtin_amdgcn_rcpf(x); }
; __device__ __forceinline__ f32x4 mfma16(bf16x8 a, bf16x8 b, f32x4 c) { return __builtin_amdgcn_mfma_f32_16x16x32_bf16(a, b, c, 0, 0, 0); }
; __device__ __forceinline__ void attn_unit(LAS unsigned char* lds, const bf16* P, bf16* Y, const float* gq, const float* gk, int b, int h, int qb, int tid, int wid, int lane, ...
;     ...
;                         const int st = 2 * p + u, sg = 8 * kt + st;
;                         if (sg > tg) {
; #pragma unroll
;                             for (int j = 0; j < 4; ++j) av[u][j] = 0.f;
;                         } else {
;                             const bf16x8 a0 = *(const LAS bf16x8*)(Ks + (16 * st + tq) * 72 + 8 * quad), a1 = *(const LAS bf16x8*)(Ks + (16 * st + tq) * 72 + 32 + 8 * quad);
;                             f32x4 z = (f32x4){0.f, 0.f, 0.f, 0.f};
;                             z = mfma16(a0, Bq0, z); z = mfma16(a1, Bq1, z);
;                             float r[4], be[4];
; #pragma unroll
;                             for (int j = 0; j < 4; ++j) { const float e = fexp2(fminf(z[j], 80.f)); const float rr = frcp(1.0f + e); r[j] = rr; be[j] = e * rr; }
;                             if (sg == tg) {
;                                 int tql = tq; asm volatile("" : "+v"(tql));
; #pragma unroll
;                                 for (int j = 0; j < 4; ++j) if (4 * quad + j >= tql) { r[j] = 1.0f; be[j] = 0.f; }
.LBB0_931:
	s_add_i32 s12, s80, 0x74
	s_cmp_gt_u32 s12, s41
	s_cselect_b64 s[12:13], -1, 0
	s_or_b64 s[12:13], s[12:13], s[10:11]
	s_and_b64 vcc, exec, s[12:13]
	s_cbranch_vccnz .LBB0_952
	s_add_i32 s10, s80, 0x75
	s_cmp_gt_u32 s10, s41
	v_mov_b32_e32 v59, 0
	s_cbranch_scc1 .LBB0_942
	ds_read_b128 v[56:59], v138 offset:11520
	ds_read_b128 v[60:63], v138 offset:11584
	s_cmp_lg_u32 s50, s76
	s_waitcnt lgkmcnt(1)
	v_mfma_f32_16x16x32_bf16 v[56:59], v[56:59], v[24:27], 0
	s_waitcnt lgkmcnt(0)
	v_mfma_f32_16x16x32_bf16 v[56:59], v[60:63], v[28:31], v[56:59]
	s_nop 7
	v_min_f32_e32 v56, 0x42a00000, v56
	v_min_f32_e32 v57, 0x42a00000, v57
	v_min_f32_e32 v60, 0x42a00000, v58
	v_min_f32_e32 v61, 0x42a00000, v59
	v_exp_f32_e32 v58, v56
	v_exp_f32_e32 v59, v57
	v_exp_f32_e32 v60, v60
	v_exp_f32_e32 v61, v61
	v_add_f32_e32 v56, 1.0, v58
	v_add_f32_e32 v57, 1.0, v59
	v_add_f32_e32 v64, 1.0, v60
	v_add_f32_e32 v65, 1.0, v61
	v_rcp_f32_e32 v62, v56
	v_rcp_f32_e32 v63, v57
	v_rcp_f32_e32 v56, v64
	v_rcp_f32_e32 v57, v65
	v_pk_mul_f32 v[58:59], v[58:59], v[62:63]
	v_pk_mul_f32 v[60:61], v[60:61], v[56:57]
	s_cbranch_scc1 .LBB0_935
	v_mov_b32_e32 v64, v91
	s_nop 0
	v_cmp_lt_i32_e64 s[12:13], v131, v64
	v_cmp_lt_i32_e64 s[14:15], v132, v64
	v_cmp_lt_i32_e64 s[10:11], v130, v64
	s_or_b64 s[12:13], s[14:15], s[12:13]
	v_cmp_lt_i32_e32 vcc, v98, v64
	s_or_b64 s[10:11], s[12:13], s[10:11]
	s_or_b64 vcc, s[10:11], vcc
	v_cndmask_b32_e64 v61, 0, v61, s[14:15]
	v_cndmask_b32_e64 v60, 0, v60, s[12:13]
	v_cndmask_b32_e64 v59, 0, v59, s[10:11]
	v_cndmask_b32_e32 v58, 0, v58, vcc
	v_cndmask_b32_e64 v56, 1.0, v56, s[12:13]
	v_cndmask_b32_e64 v63, 1.0, v63, s[10:11]
	v_cndmask_b32_e32 v62, 1.0, v62, vcc
	v_cndmask_b32_e64 v57, 1.0, v57, s[14:15]

; #define LAS __attribute__((address_space(3)))
; __device__ __forceinline__ float fexp2(float x) { return __builtin_amdgcn_exp2f(x); }
; __device__ __forceinline__ float frcp(float x) { return __builtin_amdgcn_rcpf(x); }
; __device__ __forceinline__ f32x4 mfma16(bf16x8 a, bf16x8 b, f32x4 c) { return __builtin_amdgcn_mfma_f32_16x16x32_bf16(a, b, c, 0, 0, 0); }
; __device__ __forceinline__ void attn_unit(LAS unsigned char* lds, const bf16* P, bf16* Y, const float* gq, const float* gk, int b, int h, int qb, int tid, int wid, int lane, ...
;     ...
;                         const int st = 2 * p + u, sg = 8 * kt + st;
;                         if (sg > tg) {
; #pragma unroll
;                             for (int j = 0; j < 4; ++j) av[u][j] = 0.f;
;                         } else {
;                             const bf16x8 a0 = *(const LAS bf16x8*)(Ks + (16 * st + tq) * 72 + 8 * quad), a1 = *(const LAS bf16x8*)(Ks + (16 * st + tq) * 72 + 32 + 8 * quad);
;                             f32x4 z = (f32x4){0.f, 0.f, 0.f, 0.f};
;                             z = mfma16(a0, Bq0, z); z = mfma16(a1, Bq1, z);
;                             float r[4], be[4];
; #pragma unroll
;                             for (int j = 0; j < 4; ++j) { const float e = fexp2(fminf(z[j], 80.f)); const float rr = frcp(1.0f + e); r[j] = rr; be[j] = e * rr; }
;                             if (sg == tg) {
;                                 int tql = tq; asm volatile("" : "+v"(tql));
; #pragma unroll
;                                 for (int j = 0; j < 4; ++j) if (4 * quad + j >= tql) { r[j] = 1.0f; be[j] = 0.f; }
.LBB0_943:
	ds_read_b128 v[60:63], v138 offset:9216
	ds_read_b128 v[64:67], v138 offset:9280
	s_cmp_lg_u32 s51, s76
	s_waitcnt lgkmcnt(1)
	v_mfma_f32_16x16x32_bf16 v[60:63], v[60:63], v[24:27], 0
	s_waitcnt lgkmcnt(0)
	v_mfma_f32_16x16x32_bf16 v[60:63], v[64:67], v[28:31], v[60:63]
	s_nop 7
	v_min_f32_e32 v60, 0x42a00000, v60
	v_min_f32_e32 v61, 0x42a00000, v61
	v_min_f32_e32 v64, 0x42a00000, v62
	v_min_f32_e32 v65, 0x42a00000, v63
	v_exp_f32_e32 v62, v60
	v_exp_f32_e32 v63, v61
	v_exp_f32_e32 v84, v64
	v_exp_f32_e32 v85, v65
	v_add_f32_e32 v60, 1.0, v62
	v_add_f32_e32 v61, 1.0, v63
	v_add_f32_e32 v64, 1.0, v84
	v_add_f32_e32 v65, 1.0, v85
	v_rcp_f32_e32 v66, v60
	v_rcp_f32_e32 v67, v61
	v_rcp_f32_e32 v60, v64
	v_rcp_f32_e32 v61, v65
	v_pk_mul_f32 v[64:65], v[62:63], v[66:67]
	v_pk_mul_f32 v[62:63], v[84:85], v[60:61]
	s_cbranch_scc1 .LBB0_945
	v_mov_b32_e32 v84, v91
	s_nop 0
	v_cmp_lt_i32_e64 s[12:13], v131, v84
	v_cmp_lt_i32_e64 s[14:15], v132, v84
	v_cmp_lt_i32_e64 s[10:11], v130, v84
	s_or_b64 s[12:13], s[14:15], s[12:13]
	v_cmp_lt_i32_e32 vcc, v98, v84
	s_or_b64 s[10:11], s[12:13], s[10:11]
	s_or_b64 vcc, s[10:11], vcc
	v_cndmask_b32_e64 v63, 0, v63, s[14:15]
	v_cndmask_b32_e64 v62, 0, v62, s[12:13]
	v_cndmask_b32_e64 v65, 0, v65, s[10:11]
	v_cndmask_b32_e32 v64, 0, v64, vcc
	v_cndmask_b32_e64 v60, 1.0, v60, s[12:13]
	v_cndmask_b32_e64 v67, 1.0, v67, s[10:11]
	v_cndmask_b32_e32 v66, 1.0, v66, vcc
	v_cndmask_b32_e64 v61, 1.0, v61, s[14:15]

; #define LAS __attribute__((address_space(3)))
; __device__ __forceinline__ float fexp2(float x) { return __builtin_amdgcn_exp2f(x); }
; __device__ __forceinline__ float frcp(float x) { return __builtin_amdgcn_rcpf(x); }
; __device__ __forceinline__ f32x4 mfma16(bf16x8 a, bf16x8 b, f32x4 c) { return __builtin_amdgcn_mfma_f32_16x16x32_bf16(a, b, c, 0, 0, 0); }
; __device__ __forceinline__ void attn_unit(LAS unsigned char* lds, const bf16* P, bf16* Y, const float* gq, const float* gk, int b, int h, int qb, int tid, int wid, int lane, ...
;     ...
;                         const int st = 2 * p + u, sg = 8 * kt + st;
;                         if (sg > tg) {
; #pragma unroll
;                             for (int j = 0; j < 4; ++j) av[u][j] = 0.f;
;                         } else {
;                             const bf16x8 a0 = *(const LAS bf16x8*)(Ks + (16 * st + tq) * 72 + 8 * quad), a1 = *(const LAS bf16x8*)(Ks + (16 * st + tq) * 72 + 32 + 8 * quad);
;                             f32x4 z = (f32x4){0.f, 0.f, 0.f, 0.f};
;                             z = mfma16(a0, Bq0, z); z = mfma16(a1, Bq1, z);
;                             float r[4], be[4];
; #pragma unroll
;                             for (int j = 0; j < 4; ++j) { const float e = fexp2(fminf(z[j], 80.f)); const float rr = frcp(1.0f + e); r[j] = rr; be[j] = e * rr; }
;                             if (sg == tg) {
;                                 int tql = tq; asm volatile("" : "+v"(tql));
; #pragma unroll
;                                 for (int j = 0; j < 4; ++j) if (4 * quad + j >= tql) { r[j] = 1.0f; be[j] = 0.f; }
.LBB0_952:
	s_add_i32 s12, s80, 0x72
	s_cmp_gt_u32 s12, s41
	s_cselect_b64 s[12:13], -1, 0
	s_or_b64 s[12:13], s[12:13], s[10:11]
	s_and_b64 vcc, exec, s[12:13]
	s_cbranch_vccnz .LBB0_973
	s_add_i32 s10, s80, 0x73
	s_cmp_gt_u32 s10, s41
	v_mov_b32_e32 v59, 0
	s_cbranch_scc1 .LBB0_963
	ds_read_b128 v[56:59], v140
	ds_read_b128 v[60:63], v140 offset:64
	s_cmp_lg_u32 s48, s76
	s_waitcnt lgkmcnt(1)
	v_mfma_f32_16x16x32_bf16 v[56:59], v[56:59], v[24:27], 0
	s_waitcnt lgkmcnt(0)
	v_mfma_f32_16x16x32_bf16 v[56:59], v[60:63], v[28:31], v[56:59]
	s_nop 7
	v_min_f32_e32 v56, 0x42a00000, v56
	v_min_f32_e32 v57, 0x42a00000, v57
	v_min_f32_e32 v60, 0x42a00000, v58
	v_min_f32_e32 v61, 0x42a00000, v59
	v_exp_f32_e32 v58, v56
	v_exp_f32_e32 v59, v57
	v_exp_f32_e32 v60, v60
	v_exp_f32_e32 v61, v61
	v_add_f32_e32 v56, 1.0, v58
	v_add_f32_e32 v57, 1.0, v59
	v_add_f32_e32 v64, 1.0, v60
	v_add_f32_e32 v65, 1.0, v61
	v_rcp_f32_e32 v62, v56
	v_rcp_f32_e32 v63, v57
	v_rcp_f32_e32 v56, v64
	v_rcp_f32_e32 v57, v65
	v_pk_mul_f32 v[58:59], v[58:59], v[62:63]
	v_pk_mul_f32 v[60:61], v[60:61], v[56:57]
	s_cbranch_scc1 .LBB0_956
	v_mov_b32_e32 v64, v91
	s_nop 0
	v_cmp_lt_i32_e64 s[12:13], v131, v64
	v_cmp_lt_i32_e64 s[14:15], v132, v64
	v_cmp_lt_i32_e64 s[10:11], v130, v64
	s_or_b64 s[12:13], s[14:15], s[12:13]
	v_cmp_lt_i32_e32 vcc, v98, v64
	s_or_b64 s[10:11], s[12:13], s[10:11]
	s_or_b64 vcc, s[10:11], vcc
	v_cndmask_b32_e64 v61, 0, v61, s[14:15]
	v_cndmask_b32_e64 v60, 0, v60, s[12:13]
	v_cndmask_b32_e64 v59, 0, v59, s[10:11]
	v_cndmask_b32_e32 v58, 0, v58, vcc
	v_cndmask_b32_e64 v56, 1.0, v56, s[12:13]
	v_cndmask_b32_e64 v63, 1.0, v63, s[10:11]
	v_cndmask_b32_e32 v62, 1.0, v62, vcc
	v_cndmask_b32_e64 v57, 1.0, v57, s[14:15]

; #define LAS __attribute__((address_space(3)))
; __device__ __forceinline__ float fexp2(float x) { return __builtin_amdgcn_exp2f(x); }
; __device__ __forceinline__ float frcp(float x) { return __builtin_amdgcn_rcpf(x); }
; __device__ __forceinline__ f32x4 mfma16(bf16x8 a, bf16x8 b, f32x4 c) { return __builtin_amdgcn_mfma_f32_16x16x32_bf16(a, b, c, 0, 0, 0); }
; __device__ __forceinline__ void attn_unit(LAS unsigned char* lds, const bf16* P, bf16* Y, const float* gq, const float* gk, int b, int h, int qb, int tid, int wid, int lane, ...
;     ...
;                         const int st = 2 * p + u, sg = 8 * kt + st;
;                         if (sg > tg) {
; #pragma unroll
;                             for (int j = 0; j < 4; ++j) av[u][j] = 0.f;
;                         } else {
;                             const bf16x8 a0 = *(const LAS bf16x8*)(Ks + (16 * st + tq) * 72 + 8 * quad), a1 = *(const LAS bf16x8*)(Ks + (16 * st + tq) * 72 + 32 + 8 * quad);
;                             f32x4 z = (f32x4){0.f, 0.f, 0.f, 0.f};
;                             z = mfma16(a0, Bq0, z); z = mfma16(a1, Bq1, z);
;                             float r[4], be[4];
; #pragma unroll
;                             for (int j = 0; j < 4; ++j) { const float e = fexp2(fminf(z[j], 80.f)); const float rr = frcp(1.0f + e); r[j] = rr; be[j] = e * rr; }
;                             if (sg == tg) {
;                                 int tql = tq; asm volatile("" : "+v"(tql));
; #pragma unroll
;                                 for (int j = 0; j < 4; ++j) if (4 * quad + j >= tql) { r[j] = 1.0f; be[j] = 0.f; }
.LBB0_964:
	ds_read_b128 v[60:63], v141
	ds_read_b128 v[64:67], v141 offset:64
	s_cmp_lg_u32 s49, s76
	s_waitcnt lgkmcnt(1)
	v_mfma_f32_16x16x32_bf16 v[60:63], v[60:63], v[24:27], 0
	s_waitcnt lgkmcnt(0)
	v_mfma_f32_16x16x32_bf16 v[60:63], v[64:67], v[28:31], v[60:63]
	s_nop 7
	v_min_f32_e32 v60, 0x42a00000, v60
	v_min_f32_e32 v61, 0x42a00000, v61
	v_min_f32_e32 v64, 0x42a00000, v62
	v_min_f32_e32 v65, 0x42a00000, v63
	v_exp_f32_e32 v62, v60
	v_exp_f32_e32 v63, v61
	v_exp_f32_e32 v84, v64
	v_exp_f32_e32 v85, v65
	v_add_f32_e32 v60, 1.0, v62
	v_add_f32_e32 v61, 1.0, v63
	v_add_f32_e32 v64, 1.0, v84
	v_add_f32_e32 v65, 1.0, v85
	v_rcp_f32_e32 v66, v60
	v_rcp_f32_e32 v67, v61
	v_rcp_f32_e32 v60, v64
	v_rcp_f32_e32 v61, v65
	v_pk_mul_f32 v[64:65], v[62:63], v[66:67]
	v_pk_mul_f32 v[62:63], v[84:85], v[60:61]
	s_cbranch_scc1 .LBB0_966
	v_mov_b32_e32 v84, v91
	s_nop 0
	v_cmp_lt_i32_e64 s[12:13], v131, v84
	v_cmp_lt_i32_e64 s[14:15], v132, v84
	v_cmp_lt_i32_e64 s[10:11], v130, v84
	s_or_b64 s[12:13], s[14:15], s[12:13]
	v_cmp_lt_i32_e32 vcc, v98, v84
	s_or_b64 s[10:11], s[12:13], s[10:11]
	s_or_b64 vcc, s[10:11], vcc
	v_cndmask_b32_e64 v63, 0, v63, s[14:15]
	v_cndmask_b32_e64 v62, 0, v62, s[12:13]
	v_cndmask_b32_e64 v65, 0, v65, s[10:11]
	v_cndmask_b32_e32 v64, 0, v64, vcc
	v_cndmask_b32_e64 v60, 1.0, v60, s[12:13]
	v_cndmask_b32_e64 v67, 1.0, v67, s[10:11]
	v_cndmask_b32_e32 v66, 1.0, v66, vcc
	v_cndmask_b32_e64 v61, 1.0, v61, s[14:15]

; #define LAS __attribute__((address_space(3)))
; __device__ __forceinline__ float fexp2(float x) { return __builtin_amdgcn_exp2f(x); }
; __device__ __forceinline__ float frcp(float x) { return __builtin_amdgcn_rcpf(x); }
; __device__ __forceinline__ f32x4 mfma16(bf16x8 a, bf16x8 b, f32x4 c) { return __builtin_amdgcn_mfma_f32_16x16x32_bf16(a, b, c, 0, 0, 0); }
; __device__ __forceinline__ void attn_unit(LAS unsigned char* lds, const bf16* P, bf16* Y, const float* gq, const float* gk, int b, int h, int qb, int tid, int wid, int lane, ...
;     ...
;                         const int st = 2 * p + u, sg = 8 * kt + st;
;                         if (sg > tg) {
; #pragma unroll
;                             for (int j = 0; j < 4; ++j) av[u][j] = 0.f;
;                         } else {
;                             const bf16x8 a0 = *(const LAS bf16x8*)(Ks + (16 * st + tq) * 72 + 8 * quad), a1 = *(const LAS bf16x8*)(Ks + (16 * st + tq) * 72 + 32 + 8 * quad);
;                             f32x4 z = (f32x4){0.f, 0.f, 0.f, 0.f};
;                             z = mfma16(a0, Bq0, z); z = mfma16(a1, Bq1, z);
;                             float r[4], be[4];
; #pragma unroll
;                             for (int j = 0; j < 4; ++j) { const float e = fexp2(fminf(z[j], 80.f)); const float rr = frcp(1.0f + e); r[j] = rr; be[j] = e * rr; }
;                             if (sg == tg) {
;                                 int tql = tq; asm volatile("" : "+v"(tql));
; #pragma unroll
;                                 for (int j = 0; j < 4; ++j) if (4 * quad + j >= tql) { r[j] = 1.0f; be[j] = 0.f; }
.LBB0_973:
	s_addk_i32 s80, 0x70
	s_cmp_gt_u32 s80, s41
	s_cselect_b64 s[12:13], -1, 0
	s_or_b64 s[12:13], s[12:13], s[10:11]
	s_and_b64 vcc, exec, s[12:13]
	s_cbranch_vccnz .LBB0_994
	s_cmp_ge_u32 s80, s41
	v_mov_b32_e32 v59, 0
	s_cbranch_scc1 .LBB0_984
	ds_read_b128 v[56:59], v138 offset:2304
	ds_read_b128 v[60:63], v138 offset:2368
	s_cmp_lg_u32 s3, s76
	s_waitcnt lgkmcnt(1)
	v_mfma_f32_16x16x32_bf16 v[56:59], v[56:59], v[24:27], 0
	s_waitcnt lgkmcnt(0)
	v_mfma_f32_16x16x32_bf16 v[56:59], v[60:63], v[28:31], v[56:59]
	s_nop 7
	v_min_f32_e32 v56, 0x42a00000, v56
	v_min_f32_e32 v57, 0x42a00000, v57
	v_min_f32_e32 v60, 0x42a00000, v58
	v_min_f32_e32 v61, 0x42a00000, v59
	v_exp_f32_e32 v58, v56
	v_exp_f32_e32 v59, v57
	v_exp_f32_e32 v60, v60
	v_exp_f32_e32 v61, v61
	v_add_f32_e32 v56, 1.0, v58
	v_add_f32_e32 v57, 1.0, v59
	v_add_f32_e32 v64, 1.0, v60
	v_add_f32_e32 v65, 1.0, v61
	v_rcp_f32_e32 v62, v56
	v_rcp_f32_e32 v63, v57
	v_rcp_f32_e32 v56, v64
	v_rcp_f32_e32 v57, v65
	v_pk_mul_f32 v[58:59], v[58:59], v[62:63]
	v_pk_mul_f32 v[60:61], v[60:61], v[56:57]
	s_cbranch_scc1 .LBB0_977
	v_mov_b32_e32 v64, v91
	s_nop 0
	v_cmp_lt_i32_e64 s[12:13], v131, v64
	v_cmp_lt_i32_e64 s[14:15], v132, v64
	v_cmp_lt_i32_e64 s[10:11], v130, v64
	s_or_b64 s[12:13], s[14:15], s[12:13]
	v_cmp_lt_i32_e32 vcc, v98, v64
	s_or_b64 s[10:11], s[12:13], s[10:11]
	s_or_b64 vcc, s[10:11], vcc
	v_cndmask_b32_e64 v61, 0, v61, s[14:15]
	v_cndmask_b32_e64 v60, 0, v60, s[12:13]
	v_cndmask_b32_e64 v59, 0, v59, s[10:11]
	v_cndmask_b32_e32 v58, 0, v58, vcc
	v_cndmask_b32_e64 v56, 1.0, v56, s[12:13]
	v_cndmask_b32_e64 v63, 1.0, v63, s[10:11]
	v_cndmask_b32_e32 v62, 1.0, v62, vcc
	v_cndmask_b32_e64 v57, 1.0, v57, s[14:15]

; #define LAS __attribute__((address_space(3)))
; __device__ __forceinline__ float fexp2(float x) { return __builtin_amdgcn_exp2f(x); }
; __device__ __forceinline__ float frcp(float x) { return __builtin_amdgcn_rcpf(x); }
; __device__ __forceinline__ f32x4 mfma16(bf16x8 a, bf16x8 b, f32x4 c) { return __builtin_amdgcn_mfma_f32_16x16x32_bf16(a, b, c, 0, 0, 0); }
; __device__ __forceinline__ void attn_unit(LAS unsigned char* lds, const bf16* P, bf16* Y, const float* gq, const float* gk, int b, int h, int qb, int tid, int wid, int lane, ...
;     ...
;                         const int st = 2 * p + u, sg = 8 * kt + st;
;                         if (sg > tg) {
; #pragma unroll
;                             for (int j = 0; j < 4; ++j) av[u][j] = 0.f;
;                         } else {
;                             const bf16x8 a0 = *(const LAS bf16x8*)(Ks + (16 * st + tq) * 72 + 8 * quad), a1 = *(const LAS bf16x8*)(Ks + (16 * st + tq) * 72 + 32 + 8 * quad);
;                             f32x4 z = (f32x4){0.f, 0.f, 0.f, 0.f};
;                             z = mfma16(a0, Bq0, z); z = mfma16(a1, Bq1, z);
;                             float r[4], be[4];
; #pragma unroll
;                             for (int j = 0; j < 4; ++j) { const float e = fexp2(fminf(z[j], 80.f)); const float rr = frcp(1.0f + e); r[j] = rr; be[j] = e * rr; }
;                             if (sg == tg) {
;                                 int tql = tq; asm volatile("" : "+v"(tql));
; #pragma unroll
;                                 for (int j = 0; j < 4; ++j) if (4 * quad + j >= tql) { r[j] = 1.0f; be[j] = 0.f; }
.LBB0_985:
	ds_read_b128 v[60:63], v138
	ds_read_b128 v[64:67], v138 offset:64
	s_cmp_lg_u32 s33, s76
	s_waitcnt lgkmcnt(1)
	v_mfma_f32_16x16x32_bf16 v[60:63], v[60:63], v[24:27], 0
	s_waitcnt lgkmcnt(0)
	v_mfma_f32_16x16x32_bf16 v[60:63], v[64:67], v[28:31], v[60:63]
	s_nop 7
	v_min_f32_e32 v60, 0x42a00000, v60
	v_min_f32_e32 v61, 0x42a00000, v61
	v_min_f32_e32 v64, 0x42a00000, v62
	v_min_f32_e32 v65, 0x42a00000, v63
	v_exp_f32_e32 v62, v60
	v_exp_f32_e32 v63, v61
	v_exp_f32_e32 v84, v64
	v_exp_f32_e32 v85, v65
	v_add_f32_e32 v60, 1.0, v62
	v_add_f32_e32 v61, 1.0, v63
	v_add_f32_e32 v64, 1.0, v84
	v_add_f32_e32 v65, 1.0, v85
	v_rcp_f32_e32 v66, v60
	v_rcp_f32_e32 v67, v61
	v_rcp_f32_e32 v60, v64
	v_rcp_f32_e32 v61, v65
	v_pk_mul_f32 v[64:65], v[62:63], v[66:67]
	v_pk_mul_f32 v[62:63], v[84:85], v[60:61]
	s_cbranch_scc1 .LBB0_987
	v_mov_b32_e32 v84, v91
	s_nop 0
	v_cmp_lt_i32_e64 s[12:13], v131, v84
	v_cmp_lt_i32_e64 s[14:15], v132, v84
	v_cmp_lt_i32_e64 s[10:11], v130, v84
	s_or_b64 s[12:13], s[14:15], s[12:13]
	v_cmp_lt_i32_e32 vcc, v98, v84
	s_or_b64 s[10:11], s[12:13], s[10:11]
	s_or_b64 vcc, s[10:11], vcc
	v_cndmask_b32_e64 v63, 0, v63, s[14:15]
	v_cndmask_b32_e64 v62, 0, v62, s[12:13]
	v_cndmask_b32_e64 v65, 0, v65, s[10:11]
	v_cndmask_b32_e32 v64, 0, v64, vcc
	v_cndmask_b32_e64 v60, 1.0, v60, s[12:13]
	v_cndmask_b32_e64 v67, 1.0, v67, s[10:11]
	v_cndmask_b32_e32 v66, 1.0, v66, vcc
	v_cndmask_b32_e64 v61, 1.0, v61, s[14:15]
